# rebalance LDS-DMA staging in the P1 and P6 GEMM K-loops from 2/6/2/6 to 4/4/4/4 pieces per phase (A half-0 slots staged one phase later), vmcnt re-derived
# speedup vs baseline: 1.0006x; 1.0006x over previous
; #define PG8_STAGE(bufoff, gbase, voff) do { const char* _gb = (const char*)(gbase); asm volatile("" : "+s"(_gb));     \
;         _Pragma("unroll") for (int _i = 0; _i < 2; ++_i) \
;         __builtin_amdgcn_global_load_lds((const unsigned*)(_gb + (voff)[_i]), (LAS unsigned*)(lds + (bufoff) + ldsw + _i * 8192), 16, 0, 0); } while (0)
; #define PG8_VOFF_OPAQUE asm volatile("" : "+v"(voffA[0]), "+v"(voffA[1]), "+v"(voffB[0]), "+v"(voffB[1]))
; #define PG8_LDA(dst, b, h) do { _Pragma("unroll") for (int m = 0; m < 4; ++m) _Pragma("unroll") for (int k = 0; k < 2; ++k) dst[m][k] = *(const LAS bf16x8*)(lds + PG8_SA(b, h) + aoff + m * 2048 + k * 1024); } while (0)
; #define PG8_LDB(dst, b, h) do { _Pragma("unroll") for (int n = 0; n < 2; ++n) _Pragma("unroll") for (int k = 0; k < 2; ++k) dst[n][k] = *(const LAS bf16x8*)(lds + PG8_SB(b, h) + boff + n * 2048 + k * 1024); } while (0)
; #define PG8_SCHED __builtin_amdgcn_sched_barrier(0)
; template <class Epi>
; __device__ __forceinline__ void gemm_phase(LAS unsigned char* lds, const Gemm g, const StaticOrder& S, const Epi& E) {
;     ...
;         const bool has_next = S.next(ui + 1, nxt);
;         const char* nA = has_next ? (const char*)gA + (size_t)nxt.pm * tstepA + (size_t)nxt.pn * acolb + (size_t)nxt.kofs * kstepA : cA; const char* nB = has_next ? (const char*)gB + (size_t)nxt.pn * tstepB + (size_t)nxt.kofs * kstepB : cB;
;         const int nt = cur.nt;
;         for (int t = 0; t < nt; t += 2) {
;             PG8_VOFF_OPAQUE;
;             const bool last = (t == nt - 2);
;             const char* a1 = cA + (size_t)(t + 1) * kstepA;
;             const char* a2 = last ? nA : cA + (size_t)(t + 2) * kstepA; const char* b2 = last ? nB : cB + (size_t)(t + 2) * kstepB;
;             const char* a3 = a2 + kstepA; const char* b3 = b2 + kstepB;
;             PG8_LDB(B0, 0, 0); PG8_LDB(B1, 0, 1); PG8_SCHED; PG8_LDA(At, 0, 0); PG8_STAGE(PG8_SA(1, 1), a1 + hstepA, voffA);
;     ...
;         for (int a = 0; a < 2; ++a)
; #pragma unroll
;             for (int b = 0; b < 2; ++b)
; #pragma unroll
;                 for (int m = 0; m < 4; ++m)
; #pragma unroll
;                     for (int n = 0; n < 2; ++n) acc[a][b][m][n] = (f32x4){0.f, 0.f, 0.f, 0.f};
;         cur = nxt; cA = nA; cB = nB; ++ui;
.LBB0_108:
	s_ashr_i32 s41, s40, 31
	s_lshl_b64 s[44:45], s[40:41], 20
	s_add_u32 s44, s10, s44
	s_addc_u32 s45, s11, s45
	s_and_b64 s[6:7], s[6:7], exec
	s_cselect_b32 s41, s45, s51
	s_cselect_b32 s62, s44, s50
	s_add_u32 s63, s48, 0x100
	s_addc_u32 s64, s49, 0
	s_add_u32 s65, s50, 0x100
	v_mov_b32_e32 v0, 0
	s_addc_u32 s66, s51, 0
	s_mov_b32 s67, -2
	v_mov_b32_e32 v1, v0
	v_mov_b32_e32 v2, v0
	v_mov_b32_e32 v3, v0
	v_mov_b32_e32 v4, v0
	v_mov_b32_e32 v5, v0
	v_mov_b32_e32 v6, v0
	v_mov_b32_e32 v7, v0
	v_mov_b32_e32 v16, v0
	v_mov_b32_e32 v17, v0
	v_mov_b32_e32 v18, v0
	v_mov_b32_e32 v19, v0
	v_mov_b32_e32 v20, v0
	v_mov_b32_e32 v21, v0
	v_mov_b32_e32 v22, v0
	v_mov_b32_e32 v23, v0
	v_mov_b32_e32 v32, v0
	v_mov_b32_e32 v33, v0
	v_mov_b32_e32 v34, v0
	v_mov_b32_e32 v35, v0
	v_mov_b32_e32 v36, v0
	v_mov_b32_e32 v37, v0
	v_mov_b32_e32 v38, v0
	v_mov_b32_e32 v39, v0
	v_mov_b32_e32 v48, v0
	v_mov_b32_e32 v49, v0
	v_mov_b32_e32 v50, v0
	v_mov_b32_e32 v51, v0
	v_mov_b32_e32 v52, v0
	v_mov_b32_e32 v53, v0
	v_mov_b32_e32 v54, v0
	v_mov_b32_e32 v55, v0
	v_mov_b32_e32 v8, v0
	v_mov_b32_e32 v9, v0
	v_mov_b32_e32 v10, v0
	v_mov_b32_e32 v11, v0
	v_mov_b32_e32 v12, v0
	v_mov_b32_e32 v13, v0
	v_mov_b32_e32 v14, v0
	v_mov_b32_e32 v15, v0
	v_mov_b32_e32 v24, v0
	v_mov_b32_e32 v25, v0
	v_mov_b32_e32 v26, v0
	v_mov_b32_e32 v27, v0
	v_mov_b32_e32 v28, v0
	v_mov_b32_e32 v29, v0
	v_mov_b32_e32 v30, v0
	v_mov_b32_e32 v31, v0
	v_mov_b32_e32 v40, v0
	v_mov_b32_e32 v41, v0
	v_mov_b32_e32 v42, v0
	v_mov_b32_e32 v43, v0
	v_mov_b32_e32 v44, v0
	v_mov_b32_e32 v45, v0
	v_mov_b32_e32 v46, v0
	v_mov_b32_e32 v47, v0
	v_mov_b32_e32 v56, v0
	v_mov_b32_e32 v57, v0
	v_mov_b32_e32 v58, v0
	v_mov_b32_e32 v59, v0
	v_mov_b32_e32 v60, v0
	v_mov_b32_e32 v61, v0
	v_mov_b32_e32 v62, v0
	v_mov_b32_e32 v63, v0
	v_mov_b32_e32 v64, v0
	v_mov_b32_e32 v65, v0
	v_mov_b32_e32 v66, v0
	v_mov_b32_e32 v67, v0
	v_mov_b32_e32 v68, v0
	v_mov_b32_e32 v69, v0
	v_mov_b32_e32 v70, v0
	v_mov_b32_e32 v71, v0
	v_mov_b32_e32 v80, v0
	v_mov_b32_e32 v81, v0
	v_mov_b32_e32 v82, v0
	v_mov_b32_e32 v83, v0
	v_mov_b32_e32 v84, v0
	v_mov_b32_e32 v85, v0
	v_mov_b32_e32 v86, v0
	v_mov_b32_e32 v87, v0
	v_mov_b32_e32 v96, v0
	v_mov_b32_e32 v97, v0
	v_mov_b32_e32 v98, v0
	v_mov_b32_e32 v99, v0
	v_mov_b32_e32 v100, v0
	v_mov_b32_e32 v101, v0
	v_mov_b32_e32 v102, v0
	v_mov_b32_e32 v103, v0
	v_mov_b32_e32 v112, v0
	v_mov_b32_e32 v113, v0
	v_mov_b32_e32 v114, v0
	v_mov_b32_e32 v115, v0
	v_mov_b32_e32 v116, v0
	v_mov_b32_e32 v117, v0
	v_mov_b32_e32 v118, v0
	v_mov_b32_e32 v119, v0
	v_mov_b32_e32 v72, v0
	v_mov_b32_e32 v73, v0
	v_mov_b32_e32 v74, v0
	v_mov_b32_e32 v75, v0
	v_mov_b32_e32 v76, v0
	v_mov_b32_e32 v77, v0
	v_mov_b32_e32 v78, v0
	v_mov_b32_e32 v79, v0
	v_mov_b32_e32 v88, v0
	v_mov_b32_e32 v89, v0
	v_mov_b32_e32 v90, v0
	v_mov_b32_e32 v91, v0
	v_mov_b32_e32 v92, v0
	v_mov_b32_e32 v93, v0
	v_mov_b32_e32 v94, v0
	v_mov_b32_e32 v95, v0
	v_mov_b32_e32 v104, v0
	v_mov_b32_e32 v105, v0
	v_mov_b32_e32 v106, v0
	v_mov_b32_e32 v107, v0
	v_mov_b32_e32 v108, v0
	v_mov_b32_e32 v109, v0
	v_mov_b32_e32 v110, v0
	v_mov_b32_e32 v111, v0
	v_mov_b32_e32 v120, v0
	v_mov_b32_e32 v121, v0
	v_mov_b32_e32 v122, v0
	v_mov_b32_e32 v123, v0
	v_mov_b32_e32 v124, v0
	v_mov_b32_e32 v125, v0
	v_mov_b32_e32 v126, v0
	v_mov_b32_e32 v127, v0
.LBB0_109:
	ds_read_b128 v[150:153], v135
	ds_read_b128 v[154:157], v135 offset:1024
	ds_read_b128 v[158:161], v135 offset:2048
	ds_read_b128 v[162:165], v135 offset:3072
	ds_read_b128 v[166:169], v143
	ds_read_b128 v[170:173], v143 offset:1024
	ds_read_b128 v[174:177], v143 offset:2048
	ds_read_b128 v[178:181], v143 offset:3072
	s_cmp_eq_u32 s67, 28
	s_cselect_b32 s50, s62, s65
	s_cselect_b32 s51, s41, s66
	s_cselect_b32 s48, s42, s63
	s_cselect_b32 s49, s43, s64
	s_add_u32 s6, s65, 0xffffff80
	s_addc_u32 s7, s66, -1
	s_add_u32 s52, s65, s20
	s_addc_u32 s53, s66, s21
	s_add_u32 s52, s52, 0xffffff80
	s_addc_u32 s53, s53, -1
	s_mov_b32 m0, s47
	ds_read_b128 v[182:185], v145
	ds_read_b128 v[186:189], v145 offset:1024
	ds_read_b128 v[190:193], v145 offset:2048
	ds_read_b128 v[194:197], v145 offset:3072
	ds_read_b128 v[198:201], v145 offset:4096
	ds_read_b128 v[202:205], v145 offset:5120
	ds_read_b128 v[206:209], v145 offset:6144
	ds_read_b128 v[210:213], v145 offset:7168
	s_nop 0
	global_load_lds_dwordx4 v134, s[6:7]
	s_mov_b32 m0, s54
	s_nop 0
	global_load_lds_dwordx4 v130, s[6:7]
	s_add_i32 m0, s25, 0xc000
	s_nop 0
	global_load_lds_dwordx4 v134, s[52:53]
	s_add_i32 m0, s25, 0xe000
	s_nop 0
	global_load_lds_dwordx4 v130, s[52:53]
	s_waitcnt vmcnt(8)
	s_waitcnt lgkmcnt(0)
	s_barrier
; #define PG8_STAGE(bufoff, gbase, voff) do { const char* _gb = (const char*)(gbase); asm volatile("" : "+s"(_gb));     \
;         _Pragma("unroll") for (int _i = 0; _i < 2; ++_i) \
;         __builtin_amdgcn_global_load_lds((const unsigned*)(_gb + (voff)[_i]), (LAS unsigned*)(lds + (bufoff) + ldsw + _i * 8192), 16, 0, 0); } while (0)
; #define PG8_LDA(dst, b, h) do { _Pragma("unroll") for (int m = 0; m < 4; ++m) _Pragma("unroll") for (int k = 0; k < 2; ++k) dst[m][k] = *(const LAS bf16x8*)(lds + PG8_SA(b, h) + aoff + m * 2048 + k * 1024); } while (0)
; #define PG8_WAIT_V(n) asm volatile("s_waitcnt vmcnt(" #n ")" ::: "memory")
; #define PG8_WAIT_L(n) asm volatile("s_waitcnt lgkmcnt(" #n ")" ::: "memory")
; #define PG8_BAR __builtin_amdgcn_s_barrier()
; #define PG8_SCHED __builtin_amdgcn_sched_barrier(0)
; template <class Epi>
; __device__ __forceinline__ void gemm_phase(LAS unsigned char* lds, const Gemm g, const StaticOrder& S, const Epi& E) {
;     ...
;             PG8_WAIT_V(8); PG8_WAIT_L(0); PG8_BAR; PG8_MMA2(0, At, B0, B1); PG8_BAR; PG8_SCHED;
;             PG8_LDA(At, 0, 1); PG8_STAGE(PG8_SB(0, 0), b2, voffB); PG8_STAGE(PG8_SB(0, 1), b2 + hstepB, voffB); PG8_STAGE(PG8_SA(0, 0), a2, voffA);
;             PG8_WAIT_V(8); PG8_WAIT_L(0); PG8_BAR; PG8_MMA2(1, At, B0, B1); PG8_BAR; PG8_SCHED;
	s_setprio 1
	s_waitcnt lgkmcnt(0)
	v_mfma_f32_16x16x32_bf16 v[124:127], v[150:153], v[182:185], v[124:127]
	v_mfma_f32_16x16x32_bf16 v[120:123], v[158:161], v[182:185], v[120:123]
	v_mfma_f32_16x16x32_bf16 v[108:111], v[150:153], v[190:193], v[108:111]
	v_mfma_f32_16x16x32_bf16 v[104:107], v[158:161], v[190:193], v[104:107]
	v_mfma_f32_16x16x32_bf16 v[92:95], v[150:153], v[198:201], v[92:95]
	v_mfma_f32_16x16x32_bf16 v[88:91], v[158:161], v[198:201], v[88:91]
	v_mfma_f32_16x16x32_bf16 v[76:79], v[150:153], v[206:209], v[76:79]
	v_mfma_f32_16x16x32_bf16 v[72:75], v[158:161], v[206:209], v[72:75]
	v_mfma_f32_16x16x32_bf16 v[116:119], v[166:169], v[182:185], v[116:119]
	v_mfma_f32_16x16x32_bf16 v[112:115], v[174:177], v[182:185], v[112:115]
	v_mfma_f32_16x16x32_bf16 v[100:103], v[166:169], v[190:193], v[100:103]
	v_mfma_f32_16x16x32_bf16 v[96:99], v[174:177], v[190:193], v[96:99]
	v_mfma_f32_16x16x32_bf16 v[84:87], v[166:169], v[198:201], v[84:87]
	v_mfma_f32_16x16x32_bf16 v[80:83], v[174:177], v[198:201], v[80:83]
	v_mfma_f32_16x16x32_bf16 v[68:71], v[166:169], v[206:209], v[68:71]
	v_mfma_f32_16x16x32_bf16 v[64:67], v[174:177], v[206:209], v[64:67]
	v_mfma_f32_16x16x32_bf16 v[124:127], v[154:157], v[186:189], v[124:127]
	v_mfma_f32_16x16x32_bf16 v[120:123], v[162:165], v[186:189], v[120:123]
	v_mfma_f32_16x16x32_bf16 v[108:111], v[154:157], v[194:197], v[108:111]
	v_mfma_f32_16x16x32_bf16 v[104:107], v[162:165], v[194:197], v[104:107]
	v_mfma_f32_16x16x32_bf16 v[92:95], v[154:157], v[202:205], v[92:95]
	v_mfma_f32_16x16x32_bf16 v[88:91], v[162:165], v[202:205], v[88:91]
	v_mfma_f32_16x16x32_bf16 v[76:79], v[154:157], v[210:213], v[76:79]
	v_mfma_f32_16x16x32_bf16 v[72:75], v[162:165], v[210:213], v[72:75]
	v_mfma_f32_16x16x32_bf16 v[116:119], v[170:173], v[186:189], v[116:119]
	v_mfma_f32_16x16x32_bf16 v[112:115], v[178:181], v[186:189], v[112:115]
	v_mfma_f32_16x16x32_bf16 v[100:103], v[170:173], v[194:197], v[100:103]
	v_mfma_f32_16x16x32_bf16 v[96:99], v[178:181], v[194:197], v[96:99]
	v_mfma_f32_16x16x32_bf16 v[84:87], v[170:173], v[202:205], v[84:87]
	v_mfma_f32_16x16x32_bf16 v[80:83], v[178:181], v[202:205], v[80:83]
	v_mfma_f32_16x16x32_bf16 v[68:71], v[170:173], v[210:213], v[68:71]
	v_mfma_f32_16x16x32_bf16 v[64:67], v[178:181], v[210:213], v[64:67]
	s_setprio 0
	s_barrier
	s_add_i32 s68, s57, s3
	s_mov_b64 s[52:53], s[48:49]
	s_mov_b32 m0, s68
	ds_read_b128 v[182:185], v145 offset:16384
	ds_read_b128 v[186:189], v145 offset:17408
	ds_read_b128 v[190:193], v145 offset:18432
	ds_read_b128 v[194:197], v145 offset:19456
	ds_read_b128 v[198:201], v145 offset:20480
	ds_read_b128 v[202:205], v145 offset:21504
	ds_read_b128 v[206:209], v145 offset:22528
	ds_read_b128 v[210:213], v145 offset:23552
	s_nop 0
	global_load_lds_dwordx4 v149, s[52:53]
	s_add_i32 m0, s68, 0x2000
	s_nop 0
	global_load_lds_dwordx4 v128, s[52:53]
	s_add_u32 s52, s48, s14
	s_addc_u32 s53, s49, s15
	s_add_i32 s70, s58, s3
	s_mov_b64 s[68:69], s[52:53]
	s_mov_b32 m0, s70
	s_nop 0
	global_load_lds_dwordx4 v149, s[68:69]
	s_add_i32 m0, s70, 0x2000
	s_nop 0
	global_load_lds_dwordx4 v128, s[68:69]
	s_waitcnt vmcnt(6)
	s_waitcnt lgkmcnt(0)
	s_barrier
	s_setprio 1
	s_waitcnt lgkmcnt(0)
	v_mfma_f32_16x16x32_bf16 v[60:63], v[150:153], v[182:185], v[60:63]
	v_mfma_f32_16x16x32_bf16 v[56:59], v[158:161], v[182:185], v[56:59]
	v_mfma_f32_16x16x32_bf16 v[44:47], v[150:153], v[190:193], v[44:47]
	v_mfma_f32_16x16x32_bf16 v[40:43], v[158:161], v[190:193], v[40:43]
	v_mfma_f32_16x16x32_bf16 v[28:31], v[150:153], v[198:201], v[28:31]
	v_mfma_f32_16x16x32_bf16 v[24:27], v[158:161], v[198:201], v[24:27]
	v_mfma_f32_16x16x32_bf16 v[12:15], v[150:153], v[206:209], v[12:15]
	v_mfma_f32_16x16x32_bf16 v[8:11], v[158:161], v[206:209], v[8:11]
	v_mfma_f32_16x16x32_bf16 v[52:55], v[166:169], v[182:185], v[52:55]
	v_mfma_f32_16x16x32_bf16 v[48:51], v[174:177], v[182:185], v[48:51]
	v_mfma_f32_16x16x32_bf16 v[36:39], v[166:169], v[190:193], v[36:39]
	v_mfma_f32_16x16x32_bf16 v[32:35], v[174:177], v[190:193], v[32:35]
	v_mfma_f32_16x16x32_bf16 v[20:23], v[166:169], v[198:201], v[20:23]
	v_mfma_f32_16x16x32_bf16 v[16:19], v[174:177], v[198:201], v[16:19]
	v_mfma_f32_16x16x32_bf16 v[4:7], v[166:169], v[206:209], v[4:7]
	v_mfma_f32_16x16x32_bf16 v[0:3], v[174:177], v[206:209], v[0:3]
	v_mfma_f32_16x16x32_bf16 v[60:63], v[154:157], v[186:189], v[60:63]
	v_mfma_f32_16x16x32_bf16 v[56:59], v[162:165], v[186:189], v[56:59]
	v_mfma_f32_16x16x32_bf16 v[44:47], v[154:157], v[194:197], v[44:47]
	v_mfma_f32_16x16x32_bf16 v[40:43], v[162:165], v[194:197], v[40:43]
	v_mfma_f32_16x16x32_bf16 v[28:31], v[154:157], v[202:205], v[28:31]
	v_mfma_f32_16x16x32_bf16 v[24:27], v[162:165], v[202:205], v[24:27]
	v_mfma_f32_16x16x32_bf16 v[12:15], v[154:157], v[210:213], v[12:15]
	v_mfma_f32_16x16x32_bf16 v[8:11], v[162:165], v[210:213], v[8:11]
	v_mfma_f32_16x16x32_bf16 v[52:55], v[170:173], v[186:189], v[52:55]
	v_mfma_f32_16x16x32_bf16 v[48:51], v[178:181], v[186:189], v[48:51]
	v_mfma_f32_16x16x32_bf16 v[36:39], v[170:173], v[194:197], v[36:39]
	v_mfma_f32_16x16x32_bf16 v[32:35], v[178:181], v[194:197], v[32:35]
	v_mfma_f32_16x16x32_bf16 v[20:23], v[170:173], v[202:205], v[20:23]
	v_mfma_f32_16x16x32_bf16 v[16:19], v[178:181], v[202:205], v[16:19]
	v_mfma_f32_16x16x32_bf16 v[4:7], v[170:173], v[210:213], v[4:7]
	v_mfma_f32_16x16x32_bf16 v[0:3], v[178:181], v[210:213], v[0:3]
	s_setprio 0
	s_barrier
; #define PG8_STAGE(bufoff, gbase, voff) do { const char* _gb = (const char*)(gbase); asm volatile("" : "+s"(_gb));     \
;         _Pragma("unroll") for (int _i = 0; _i < 2; ++_i) \
;         __builtin_amdgcn_global_load_lds((const unsigned*)(_gb + (voff)[_i]), (LAS unsigned*)(lds + (bufoff) + ldsw + _i * 8192), 16, 0, 0); } while (0)
; #define PG8_LDA(dst, b, h) do { _Pragma("unroll") for (int m = 0; m < 4; ++m) _Pragma("unroll") for (int k = 0; k < 2; ++k) dst[m][k] = *(const LAS bf16x8*)(lds + PG8_SA(b, h) + aoff + m * 2048 + k * 1024); } while (0)
; #define PG8_LDB(dst, b, h) do { _Pragma("unroll") for (int n = 0; n < 2; ++n) _Pragma("unroll") for (int k = 0; k < 2; ++k) dst[n][k] = *(const LAS bf16x8*)(lds + PG8_SB(b, h) + boff + n * 2048 + k * 1024); } while (0)
; #define PG8_WAIT_V(n) asm volatile("s_waitcnt vmcnt(" #n ")" ::: "memory")
; #define PG8_WAIT_L(n) asm volatile("s_waitcnt lgkmcnt(" #n ")" ::: "memory")
; #define PG8_BAR __builtin_amdgcn_s_barrier()
; #define PG8_SCHED __builtin_amdgcn_sched_barrier(0)
; template <class Epi>
; __device__ __forceinline__ void gemm_phase(LAS unsigned char* lds, const Gemm g, const StaticOrder& S, const Epi& E) {
;     ...
;             PG8_LDB(B0, 1, 0); PG8_LDB(B1, 1, 1); PG8_SCHED; PG8_LDA(At, 1, 0); PG8_STAGE(PG8_SA(0, 1), a2 + hstepA, voffA);
;             PG8_WAIT_V(8); PG8_WAIT_L(0); PG8_BAR; PG8_MMA2(0, At, B0, B1); PG8_BAR; PG8_SCHED;
;             PG8_LDA(At, 1, 1); PG8_STAGE(PG8_SB(1, 0), b3, voffB); PG8_STAGE(PG8_SB(1, 1), b3 + hstepB, voffB); PG8_STAGE(PG8_SA(1, 0), a3, voffA);
;             PG8_WAIT_V(8); PG8_WAIT_L(0); PG8_BAR; PG8_MMA2(1, At, B0, B1); PG8_BAR; PG8_SCHED;
;         }
;         if (wr == 0) PG8_BAR;
	s_add_i32 s68, 0, 0x18000
	v_add_u32_e32 v132, s68, v131
	s_add_i32 s69, 0, 0x1c000
	ds_read_b128 v[150:153], v132
	ds_read_b128 v[154:157], v132 offset:1024
	ds_read_b128 v[158:161], v132 offset:2048
	ds_read_b128 v[162:165], v132 offset:3072
	v_add_u32_e32 v132, s69, v131
	ds_read_b128 v[166:169], v132
	ds_read_b128 v[170:173], v132 offset:1024
	ds_read_b128 v[174:177], v132 offset:2048
	ds_read_b128 v[178:181], v132 offset:3072
	s_add_u32 s6, s50, s20
	s_addc_u32 s7, s51, s21
	s_mov_b32 m0, s25
	ds_read_b128 v[182:185], v145 offset:32768
	ds_read_b128 v[186:189], v145 offset:33792
	ds_read_b128 v[190:193], v145 offset:34816
	ds_read_b128 v[194:197], v145 offset:35840
	ds_read_b128 v[198:201], v145 offset:36864
	ds_read_b128 v[202:205], v145 offset:37888
	ds_read_b128 v[206:209], v145 offset:38912
	ds_read_b128 v[210:213], v145 offset:39936
	s_nop 0
	global_load_lds_dwordx4 v134, s[50:51]
	s_mov_b32 m0, s26
	s_nop 0
	global_load_lds_dwordx4 v130, s[50:51]
	s_mov_b32 m0, s27
	s_nop 0
	global_load_lds_dwordx4 v134, s[6:7]
	s_mov_b32 m0, s33
	s_nop 0
	global_load_lds_dwordx4 v130, s[6:7]
	s_waitcnt vmcnt(8)
	s_waitcnt lgkmcnt(0)
	s_barrier
	s_setprio 1
	s_waitcnt lgkmcnt(0)
	v_mfma_f32_16x16x32_bf16 v[124:127], v[150:153], v[182:185], v[124:127]
	v_mfma_f32_16x16x32_bf16 v[120:123], v[158:161], v[182:185], v[120:123]
	v_mfma_f32_16x16x32_bf16 v[108:111], v[150:153], v[190:193], v[108:111]
	v_mfma_f32_16x16x32_bf16 v[104:107], v[158:161], v[190:193], v[104:107]
	v_mfma_f32_16x16x32_bf16 v[92:95], v[150:153], v[198:201], v[92:95]
	v_mfma_f32_16x16x32_bf16 v[88:91], v[158:161], v[198:201], v[88:91]
	v_mfma_f32_16x16x32_bf16 v[76:79], v[150:153], v[206:209], v[76:79]
	v_mfma_f32_16x16x32_bf16 v[72:75], v[158:161], v[206:209], v[72:75]
	v_mfma_f32_16x16x32_bf16 v[116:119], v[166:169], v[182:185], v[116:119]
	v_mfma_f32_16x16x32_bf16 v[112:115], v[174:177], v[182:185], v[112:115]
	v_mfma_f32_16x16x32_bf16 v[100:103], v[166:169], v[190:193], v[100:103]
	v_mfma_f32_16x16x32_bf16 v[96:99], v[174:177], v[190:193], v[96:99]
	v_mfma_f32_16x16x32_bf16 v[84:87], v[166:169], v[198:201], v[84:87]
	v_mfma_f32_16x16x32_bf16 v[80:83], v[174:177], v[198:201], v[80:83]
	v_mfma_f32_16x16x32_bf16 v[68:71], v[166:169], v[206:209], v[68:71]
	v_mfma_f32_16x16x32_bf16 v[64:67], v[174:177], v[206:209], v[64:67]
	v_mfma_f32_16x16x32_bf16 v[124:127], v[154:157], v[186:189], v[124:127]
	v_mfma_f32_16x16x32_bf16 v[120:123], v[162:165], v[186:189], v[120:123]
	v_mfma_f32_16x16x32_bf16 v[108:111], v[154:157], v[194:197], v[108:111]
	v_mfma_f32_16x16x32_bf16 v[104:107], v[162:165], v[194:197], v[104:107]
	v_mfma_f32_16x16x32_bf16 v[92:95], v[154:157], v[202:205], v[92:95]
	v_mfma_f32_16x16x32_bf16 v[88:91], v[162:165], v[202:205], v[88:91]
	v_mfma_f32_16x16x32_bf16 v[76:79], v[154:157], v[210:213], v[76:79]
	v_mfma_f32_16x16x32_bf16 v[72:75], v[162:165], v[210:213], v[72:75]
	v_mfma_f32_16x16x32_bf16 v[116:119], v[170:173], v[186:189], v[116:119]
	v_mfma_f32_16x16x32_bf16 v[112:115], v[178:181], v[186:189], v[112:115]
	v_mfma_f32_16x16x32_bf16 v[100:103], v[170:173], v[194:197], v[100:103]
	v_mfma_f32_16x16x32_bf16 v[96:99], v[178:181], v[194:197], v[96:99]
	v_mfma_f32_16x16x32_bf16 v[84:87], v[170:173], v[202:205], v[84:87]
	v_mfma_f32_16x16x32_bf16 v[80:83], v[178:181], v[202:205], v[80:83]
	v_mfma_f32_16x16x32_bf16 v[68:71], v[170:173], v[210:213], v[68:71]
	v_mfma_f32_16x16x32_bf16 v[64:67], v[178:181], v[210:213], v[64:67]
	s_setprio 0
	s_barrier
	s_add_u32 s48, s48, 0x80
	s_addc_u32 s49, s49, 0
	s_add_i32 s50, s68, s3
	s_mov_b32 m0, s50
	ds_read_b128 v[182:185], v145 offset:49152
	ds_read_b128 v[186:189], v145 offset:50176
	ds_read_b128 v[190:193], v145 offset:51200
	ds_read_b128 v[194:197], v145 offset:52224
	ds_read_b128 v[198:201], v145 offset:53248
	ds_read_b128 v[202:205], v145 offset:54272
	ds_read_b128 v[206:209], v145 offset:55296
	ds_read_b128 v[210:213], v145 offset:56320
	s_nop 0
	global_load_lds_dwordx4 v149, s[48:49]
	s_add_i32 m0, s50, 0x2000
	s_nop 0
	global_load_lds_dwordx4 v128, s[48:49]
	s_add_u32 s48, s52, 0x80
	s_addc_u32 s49, s53, 0
	s_add_i32 s50, s69, s3
	s_mov_b32 m0, s50
	s_nop 0
	global_load_lds_dwordx4 v149, s[48:49]
	s_add_i32 m0, s50, 0x2000
	s_nop 0
	global_load_lds_dwordx4 v128, s[48:49]
	s_waitcnt vmcnt(6)
	s_waitcnt lgkmcnt(0)
	s_barrier
	s_setprio 1
	s_waitcnt lgkmcnt(0)
	v_mfma_f32_16x16x32_bf16 v[60:63], v[150:153], v[182:185], v[60:63]
	v_mfma_f32_16x16x32_bf16 v[56:59], v[158:161], v[182:185], v[56:59]
	v_mfma_f32_16x16x32_bf16 v[44:47], v[150:153], v[190:193], v[44:47]
	v_mfma_f32_16x16x32_bf16 v[40:43], v[158:161], v[190:193], v[40:43]
	v_mfma_f32_16x16x32_bf16 v[28:31], v[150:153], v[198:201], v[28:31]
	v_mfma_f32_16x16x32_bf16 v[24:27], v[158:161], v[198:201], v[24:27]
	v_mfma_f32_16x16x32_bf16 v[12:15], v[150:153], v[206:209], v[12:15]
	v_mfma_f32_16x16x32_bf16 v[8:11], v[158:161], v[206:209], v[8:11]
	v_mfma_f32_16x16x32_bf16 v[52:55], v[166:169], v[182:185], v[52:55]
	v_mfma_f32_16x16x32_bf16 v[48:51], v[174:177], v[182:185], v[48:51]
	v_mfma_f32_16x16x32_bf16 v[36:39], v[166:169], v[190:193], v[36:39]
	v_mfma_f32_16x16x32_bf16 v[32:35], v[174:177], v[190:193], v[32:35]
	v_mfma_f32_16x16x32_bf16 v[20:23], v[166:169], v[198:201], v[20:23]
	v_mfma_f32_16x16x32_bf16 v[16:19], v[174:177], v[198:201], v[16:19]
	v_mfma_f32_16x16x32_bf16 v[4:7], v[166:169], v[206:209], v[4:7]
	v_mfma_f32_16x16x32_bf16 v[0:3], v[174:177], v[206:209], v[0:3]
	v_mfma_f32_16x16x32_bf16 v[60:63], v[154:157], v[186:189], v[60:63]
	v_mfma_f32_16x16x32_bf16 v[56:59], v[162:165], v[186:189], v[56:59]
	v_mfma_f32_16x16x32_bf16 v[44:47], v[154:157], v[194:197], v[44:47]
	v_mfma_f32_16x16x32_bf16 v[40:43], v[162:165], v[194:197], v[40:43]
	v_mfma_f32_16x16x32_bf16 v[28:31], v[154:157], v[202:205], v[28:31]
	v_mfma_f32_16x16x32_bf16 v[24:27], v[162:165], v[202:205], v[24:27]
	v_mfma_f32_16x16x32_bf16 v[12:15], v[154:157], v[210:213], v[12:15]
	v_mfma_f32_16x16x32_bf16 v[8:11], v[162:165], v[210:213], v[8:11]
	v_mfma_f32_16x16x32_bf16 v[52:55], v[170:173], v[186:189], v[52:55]
	v_mfma_f32_16x16x32_bf16 v[48:51], v[178:181], v[186:189], v[48:51]
	v_mfma_f32_16x16x32_bf16 v[36:39], v[170:173], v[194:197], v[36:39]
	v_mfma_f32_16x16x32_bf16 v[32:35], v[178:181], v[194:197], v[32:35]
	v_mfma_f32_16x16x32_bf16 v[20:23], v[170:173], v[202:205], v[20:23]
	v_mfma_f32_16x16x32_bf16 v[16:19], v[178:181], v[202:205], v[16:19]
	v_mfma_f32_16x16x32_bf16 v[4:7], v[170:173], v[210:213], v[4:7]
	v_mfma_f32_16x16x32_bf16 v[0:3], v[178:181], v[210:213], v[0:3]
	s_setprio 0
	s_barrier
	s_add_i32 s67, s67, 2
	s_add_u32 s63, s63, 0x100
	s_addc_u32 s64, s64, 0
	s_add_u32 s65, s65, 0x100
	s_addc_u32 s66, s66, 0
	s_cmp_gt_u32 s67, 29
	s_cbranch_scc0 .LBB0_109
	s_and_b64 vcc, exec, s[36:37]
	s_cbranch_vccz .LBB0_112
	s_barrier
; __device__ __forceinline__ unsigned pk2(float lo, float hi) { unsigned r; asm volatile("v_cvt_pk_bf16_f32 %0, %1, %2" : "=v"(r) : "v"(lo), "v"(hi)); return r; }
; __device__ __forceinline__ f32x2 swiglu_pk(f32x2 g, f32x2 u, float rs) {
;     const f32x2 t = g * rs, s = t * (-1.44269504089f);
;     f32x2 e; e.x = __builtin_amdgcn_exp2f(s.x); e.y = __builtin_amdgcn_exp2f(s.y);
;     const f32x2 d = e + 1.0f; f32x2 r; r.x = __builtin_amdgcn_rcpf(d.x); r.y = __builtin_amdgcn_rcpf(d.y);
;     return (t * r) * (u * rs);
; }
;     __device__ __forceinline__ void operator()(const f32x4 (&acc)[2][2][4][2], const Unit& u, int wr, int wc, int fr, int fq) const {
;         const int row0 = u.pm * BM + wr * 64 + fr, col0 = u.pn * 128 + wc * 32 + 8 * fq;
;         float rsv[8];
; #pragma unroll
;         for (int i = 0; i < 8; ++i) rsv[i] = ss[row0 + (i >> 2) * HALF + (i & 3) * 16];
; #pragma unroll
;         for (int i = 0; i < 8; ++i) rsv[i] = __builtin_amdgcn_rsqf(rsv[i] * (1.0f / D) + EPS);
;         __builtin_amdgcn_sched_barrier(0);
; #pragma unroll
;         for (int ai = 0; ai < 2; ++ai)
; #pragma unroll
;             for (int m = 0; m < 4; ++m) {
;                 const int row = row0 + ai * HALF + m * 16;
;                 const float rs = rsv[ai * 4 + m];
;                 const f32x4 g0 = acc[ai][0][m][0], g1 = acc[ai][0][m][1], u0 = acc[ai][1][m][0], u1 = acc[ai][1][m][1];
;                 const f32x2 o0 = swiglu_pk((f32x2){g0[0], g0[1]}, (f32x2){u0[0], u0[1]}, rs), o1 = swiglu_pk((f32x2){g0[2], g0[3]}, (f32x2){u0[2], u0[3]}, rs);
;                 const f32x2 o2 = swiglu_pk((f32x2){g1[0], g1[1]}, (f32x2){u1[0], u1[1]}, rs), o3 = swiglu_pk((f32x2){g1[2], g1[3]}, (f32x2){u1[2], u1[3]}, rs);
;                 u32x4 w; w.x = pk2(o0.x, o0.y); w.y = pk2(o1.x, o1.y); w.z = pk2(o2.x, o2.y); w.w = pk2(o3.x, o3.y);
;                 __builtin_nontemporal_store(w, (u32x4*)(G + (size_t)(row >> 8) * ((size_t)BM * FF) + (size_t)(col0 >> 6) * (BM * BK) + (size_t)(row & 255) * BK + (col0 & 63)));
.LBB0_112:
	s_lshl_b32 s6, s46, 8
	s_add_i32 s41, s6, s35
	v_or_b32_e32 v154, s41, v129
	v_ashrrev_i32_e32 v155, 31, v154
	v_lshl_add_u64 v[150:151], v[154:155], 2, s[8:9]
	global_load_dword v132, v[150:151], off
	global_load_dword v141, v[150:151], off offset:64
	global_load_dword v142, v[150:151], off offset:128
	global_load_dword v144, v[150:151], off offset:192
	global_load_dword v146, v[150:151], off offset:512
	global_load_dword v148, v[150:151], off offset:576
	global_load_dword v152, v[150:151], off offset:640
	s_nop 0
	global_load_dword v150, v[150:151], off offset:704
	s_lshl_b32 s6, s61, 7
	s_or_b32 s6, s6, s39
	s_waitcnt vmcnt(0)
	v_fmamk_f32 v132, v132, 0x3a000000, v147
	v_fmamk_f32 v141, v141, 0x3a000000, v147
	v_fmamk_f32 v142, v142, 0x3a000000, v147
	v_fmamk_f32 v144, v144, 0x3a000000, v147
	v_fmamk_f32 v146, v146, 0x3a000000, v147
	v_fmamk_f32 v151, v148, 0x3a000000, v147
	v_fmamk_f32 v153, v152, 0x3a000000, v147
	v_fmamk_f32 v155, v150, 0x3a000000, v147
	v_rsq_f32_e32 v132, v132
	v_rsq_f32_e32 v156, v141
	v_rsq_f32_e32 v152, v142
	v_rsq_f32_e32 v150, v144
	v_rsq_f32_e32 v148, v146
	v_rsq_f32_e32 v146, v151
	v_rsq_f32_e32 v144, v153
	v_rsq_f32_e32 v142, v155
	v_add_u32_e32 v151, 0x80, v154
	v_pk_mul_f32 v[124:125], v[124:125], v[132:133] op_sel_hi:[1,0]
	v_pk_mul_f32 v[126:127], v[126:127], v[132:133] op_sel_hi:[1,0]
	v_pk_mul_f32 v[158:159], v[124:125], s[38:39] op_sel_hi:[1,0]
	v_pk_mul_f32 v[160:161], v[126:127], s[38:39] op_sel_hi:[1,0]
	v_exp_f32_e32 v158, v158
	v_exp_f32_e32 v159, v159
	v_exp_f32_e32 v160, v160
	v_exp_f32_e32 v161, v161
	v_pk_mul_f32 v[116:117], v[116:117], v[132:133] op_sel_hi:[1,0]
	v_pk_add_f32 v[158:159], v[158:159], 1.0 op_sel_hi:[1,0]
	v_pk_mul_f32 v[118:119], v[118:119], v[132:133] op_sel_hi:[1,0]
	v_rcp_f32_e32 v158, v158
	v_rcp_f32_e32 v159, v159
	v_pk_add_f32 v[160:161], v[160:161], 1.0 op_sel_hi:[1,0]
	v_pk_mul_f32 v[120:121], v[120:121], v[132:133] op_sel_hi:[1,0]
	v_rcp_f32_e32 v160, v160
	v_rcp_f32_e32 v161, v161
	v_pk_mul_f32 v[124:125], v[124:125], v[158:159]
	v_pk_mul_f32 v[122:123], v[122:123], v[132:133] op_sel_hi:[1,0]
	v_pk_mul_f32 v[116:117], v[116:117], v[124:125]
	v_pk_mul_f32 v[124:125], v[126:127], v[160:161]
	v_pk_mul_f32 v[126:127], v[122:123], s[38:39] op_sel_hi:[1,0]
	v_pk_mul_f32 v[118:119], v[118:119], v[124:125]
	v_pk_mul_f32 v[124:125], v[120:121], s[38:39] op_sel_hi:[1,0]
	v_exp_f32_e32 v126, v126
	v_exp_f32_e32 v124, v124
	v_exp_f32_e32 v125, v125
	v_exp_f32_e32 v127, v127
	s_ashr_i32 s6, s6, 6
	s_ashr_i32 s7, s6, 31
	v_pk_add_f32 v[124:125], v[124:125], 1.0 op_sel_hi:[1,0]
	v_pk_add_f32 v[126:127], v[126:127], 1.0 op_sel_hi:[1,0]
	v_rcp_f32_e32 v124, v124
	v_rcp_f32_e32 v125, v125
	v_rcp_f32_e32 v126, v126
	v_rcp_f32_e32 v127, v127
	s_ashr_i32 s41, s41, 8
	s_lshl_b64 s[6:7], s[6:7], 15
	s_mul_hi_i32 s46, s41, 0x2c0000
	s_mul_i32 s41, s41, 0x2c0000
	v_pk_mul_f32 v[120:121], v[120:121], v[124:125]
	v_pk_mul_f32 v[112:113], v[112:113], v[132:133] op_sel_hi:[1,0]
	s_add_u32 s41, s30, s41
	v_pk_mul_f32 v[120:121], v[112:113], v[120:121]
	v_pk_mul_f32 v[112:113], v[122:123], v[126:127]
	v_pk_mul_f32 v[114:115], v[114:115], v[132:133] op_sel_hi:[1,0]
	s_addc_u32 s46, s31, s46
	v_pk_mul_f32 v[122:123], v[114:115], v[112:113]
	v_cvt_pk_bf16_f32 v112, v116, v117
	s_add_u32 s48, s41, s6
	v_lshlrev_b32_e32 v116, 7, v154
	s_addc_u32 s49, s46, s7
	v_and_b32_e32 v132, 0x6780, v116
	v_lshl_add_u64 v[116:117], s[48:49], 0, v[132:133]
	v_mov_b32_e32 v141, v133
	v_lshl_add_u64 v[116:117], v[116:117], 0, v[140:141]
	v_cvt_pk_bf16_f32 v113, v118, v119
	v_cvt_pk_bf16_f32 v114, v120, v121
	v_cvt_pk_bf16_f32 v115, v122, v123
	global_store_dwordx4 v[116:117], v[112:115], off nt
	v_pk_mul_f32 v[108:109], v[108:109], v[156:157] op_sel_hi:[1,0]
	v_pk_mul_f32 v[110:111], v[110:111], v[156:157] op_sel_hi:[1,0]
	v_pk_mul_f32 v[112:113], v[108:109], s[38:39] op_sel_hi:[1,0]
	v_pk_mul_f32 v[114:115], v[110:111], s[38:39] op_sel_hi:[1,0]
	v_exp_f32_e32 v112, v112
	v_exp_f32_e32 v113, v113
	v_exp_f32_e32 v114, v114
	v_exp_f32_e32 v115, v115
	v_pk_mul_f32 v[100:101], v[100:101], v[156:157] op_sel_hi:[1,0]
	v_pk_add_f32 v[112:113], v[112:113], 1.0 op_sel_hi:[1,0]
	v_pk_mul_f32 v[102:103], v[102:103], v[156:157] op_sel_hi:[1,0]
	v_rcp_f32_e32 v112, v112
	v_rcp_f32_e32 v113, v113
	v_pk_add_f32 v[114:115], v[114:115], 1.0 op_sel_hi:[1,0]
	v_pk_mul_f32 v[104:105], v[104:105], v[156:157] op_sel_hi:[1,0]
	v_rcp_f32_e32 v114, v114
	v_rcp_f32_e32 v115, v115
	v_pk_mul_f32 v[108:109], v[108:109], v[112:113]
	v_pk_mul_f32 v[106:107], v[106:107], v[156:157] op_sel_hi:[1,0]
	v_pk_mul_f32 v[100:101], v[100:101], v[108:109]
	v_pk_mul_f32 v[108:109], v[110:111], v[114:115]
	v_pk_mul_f32 v[110:111], v[106:107], s[38:39] op_sel_hi:[1,0]
	v_pk_mul_f32 v[102:103], v[102:103], v[108:109]
	v_pk_mul_f32 v[108:109], v[104:105], s[38:39] op_sel_hi:[1,0]
	v_exp_f32_e32 v110, v110
	v_exp_f32_e32 v108, v108
	v_exp_f32_e32 v109, v109
	v_exp_f32_e32 v111, v111
	v_pk_mul_f32 v[96:97], v[96:97], v[156:157] op_sel_hi:[1,0]
	v_pk_mul_f32 v[98:99], v[98:99], v[156:157] op_sel_hi:[1,0]
	v_pk_add_f32 v[108:109], v[108:109], 1.0 op_sel_hi:[1,0]
	v_pk_add_f32 v[110:111], v[110:111], 1.0 op_sel_hi:[1,0]
	v_rcp_f32_e32 v108, v108
	v_rcp_f32_e32 v109, v109
	v_rcp_f32_e32 v110, v110
	v_rcp_f32_e32 v111, v111
	v_pk_mul_f32 v[104:105], v[104:105], v[108:109]
	s_nop 0
	v_pk_mul_f32 v[104:105], v[96:97], v[104:105]
	v_pk_mul_f32 v[96:97], v[106:107], v[110:111]
	s_nop 0
	v_pk_mul_f32 v[106:107], v[98:99], v[96:97]
	v_cvt_pk_bf16_f32 v96, v100, v101
	v_cvt_pk_bf16_f32 v97, v102, v103
	v_cvt_pk_bf16_f32 v98, v104, v105
	s_nop 0
; __device__ __forceinline__ unsigned pk2(float lo, float hi) { unsigned r; asm volatile("v_cvt_pk_bf16_f32 %0, %1, %2" : "=v"(r) : "v"(lo), "v"(hi)); return r; }
; __device__ __forceinline__ f32x2 swiglu_pk(f32x2 g, f32x2 u, float rs) {
;     const f32x2 t = g * rs, s = t * (-1.44269504089f);
;     f32x2 e; e.x = __builtin_amdgcn_exp2f(s.x); e.y = __builtin_amdgcn_exp2f(s.y);
;     const f32x2 d = e + 1.0f; f32x2 r; r.x = __builtin_amdgcn_rcpf(d.x); r.y = __builtin_amdgcn_rcpf(d.y);
;     return (t * r) * (u * rs);
; }
;     __device__ __forceinline__ void operator()(const f32x4 (&acc)[2][2][4][2], const Unit& u, int wr, int wc, int fr, int fq) const {
;     ...
; #pragma unroll
;         for (int ai = 0; ai < 2; ++ai)
; #pragma unroll
;             for (int m = 0; m < 4; ++m) {
;                 const int row = row0 + ai * HALF + m * 16;
;                 const float rs = rsv[ai * 4 + m];
;                 const f32x4 g0 = acc[ai][0][m][0], g1 = acc[ai][0][m][1], u0 = acc[ai][1][m][0], u1 = acc[ai][1][m][1];
;                 const f32x2 o0 = swiglu_pk((f32x2){g0[0], g0[1]}, (f32x2){u0[0], u0[1]}, rs), o1 = swiglu_pk((f32x2){g0[2], g0[3]}, (f32x2){u0[2], u0[3]}, rs);
;                 const f32x2 o2 = swiglu_pk((f32x2){g1[0], g1[1]}, (f32x2){u1[0], u1[1]}, rs), o3 = swiglu_pk((f32x2){g1[2], g1[3]}, (f32x2){u1[2], u1[3]}, rs);
;                 u32x4 w; w.x = pk2(o0.x, o0.y); w.y = pk2(o1.x, o1.y); w.z = pk2(o2.x, o2.y); w.w = pk2(o3.x, o3.y);
;                 __builtin_nontemporal_store(w, (u32x4*)(G + (size_t)(row >> 8) * ((size_t)BM * FF) + (size_t)(col0 >> 6) * (BM * BK) + (size_t)(row & 255) * BK + (col0 & 63)));
;                 __builtin_amdgcn_sched_barrier(0);
;             }
	v_cvt_pk_bf16_f32 v99, v106, v107
	global_store_dwordx4 v[116:117], v[96:99], off offset:2048 nt
	v_pk_mul_f32 v[92:93], v[92:93], v[152:153] op_sel_hi:[1,0]
	v_pk_mul_f32 v[94:95], v[94:95], v[152:153] op_sel_hi:[1,0]
	v_pk_mul_f32 v[96:97], v[92:93], s[38:39] op_sel_hi:[1,0]
	v_pk_mul_f32 v[98:99], v[94:95], s[38:39] op_sel_hi:[1,0]
	v_exp_f32_e32 v96, v96
	v_exp_f32_e32 v97, v97
	v_exp_f32_e32 v98, v98
	v_exp_f32_e32 v99, v99
	v_pk_mul_f32 v[84:85], v[84:85], v[152:153] op_sel_hi:[1,0]
	v_pk_add_f32 v[96:97], v[96:97], 1.0 op_sel_hi:[1,0]
	v_pk_mul_f32 v[86:87], v[86:87], v[152:153] op_sel_hi:[1,0]
	v_rcp_f32_e32 v96, v96
	v_rcp_f32_e32 v97, v97
	v_pk_add_f32 v[98:99], v[98:99], 1.0 op_sel_hi:[1,0]
	v_pk_mul_f32 v[88:89], v[88:89], v[152:153] op_sel_hi:[1,0]
	v_rcp_f32_e32 v98, v98
	v_rcp_f32_e32 v99, v99
	v_pk_mul_f32 v[92:93], v[92:93], v[96:97]
	v_pk_mul_f32 v[90:91], v[90:91], v[152:153] op_sel_hi:[1,0]
	v_pk_mul_f32 v[84:85], v[84:85], v[92:93]
	v_pk_mul_f32 v[92:93], v[94:95], v[98:99]
	v_pk_mul_f32 v[94:95], v[90:91], s[38:39] op_sel_hi:[1,0]
	v_pk_mul_f32 v[86:87], v[86:87], v[92:93]
	v_pk_mul_f32 v[92:93], v[88:89], s[38:39] op_sel_hi:[1,0]
	v_exp_f32_e32 v94, v94
	v_exp_f32_e32 v92, v92
	v_exp_f32_e32 v93, v93
	v_exp_f32_e32 v95, v95
	v_pk_mul_f32 v[80:81], v[80:81], v[152:153] op_sel_hi:[1,0]
	v_pk_mul_f32 v[82:83], v[82:83], v[152:153] op_sel_hi:[1,0]
	v_pk_add_f32 v[92:93], v[92:93], 1.0 op_sel_hi:[1,0]
	v_pk_add_f32 v[94:95], v[94:95], 1.0 op_sel_hi:[1,0]
	v_rcp_f32_e32 v92, v92
	v_rcp_f32_e32 v93, v93
	v_rcp_f32_e32 v94, v94
	v_rcp_f32_e32 v95, v95
	v_pk_mul_f32 v[88:89], v[88:89], v[92:93]
	s_nop 0
	v_pk_mul_f32 v[88:89], v[80:81], v[88:89]
	v_pk_mul_f32 v[80:81], v[90:91], v[94:95]
	s_nop 0
	v_pk_mul_f32 v[90:91], v[82:83], v[80:81]
	v_cvt_pk_bf16_f32 v80, v84, v85
	v_add_co_u32_e32 v84, vcc, s59, v116
	v_cvt_pk_bf16_f32 v81, v86, v87
	v_cvt_pk_bf16_f32 v82, v88, v89
	v_cvt_pk_bf16_f32 v83, v90, v91
	s_nop 1
	v_addc_co_u32_e32 v85, vcc, 0, v117, vcc
	global_store_dwordx4 v[84:85], v[80:83], off nt
	v_pk_mul_f32 v[76:77], v[76:77], v[150:151] op_sel_hi:[1,0]
	v_pk_mul_f32 v[78:79], v[78:79], v[150:151] op_sel_hi:[1,0]
	v_pk_mul_f32 v[80:81], v[76:77], s[38:39] op_sel_hi:[1,0]
	v_pk_mul_f32 v[82:83], v[78:79], s[38:39] op_sel_hi:[1,0]
	v_exp_f32_e32 v80, v80
	v_exp_f32_e32 v81, v81
	v_exp_f32_e32 v82, v82
	v_exp_f32_e32 v83, v83
	v_pk_mul_f32 v[68:69], v[68:69], v[150:151] op_sel_hi:[1,0]
	v_pk_add_f32 v[80:81], v[80:81], 1.0 op_sel_hi:[1,0]
	v_pk_mul_f32 v[70:71], v[70:71], v[150:151] op_sel_hi:[1,0]
	v_rcp_f32_e32 v80, v80
	v_rcp_f32_e32 v81, v81
	v_pk_add_f32 v[82:83], v[82:83], 1.0 op_sel_hi:[1,0]
	v_pk_mul_f32 v[72:73], v[72:73], v[150:151] op_sel_hi:[1,0]
	v_rcp_f32_e32 v82, v82
	v_rcp_f32_e32 v83, v83
	v_pk_mul_f32 v[76:77], v[76:77], v[80:81]
	v_pk_mul_f32 v[74:75], v[74:75], v[150:151] op_sel_hi:[1,0]
	v_pk_mul_f32 v[68:69], v[68:69], v[76:77]
	v_pk_mul_f32 v[76:77], v[78:79], v[82:83]
	v_pk_mul_f32 v[78:79], v[74:75], s[38:39] op_sel_hi:[1,0]
	v_pk_mul_f32 v[70:71], v[70:71], v[76:77]
	v_pk_mul_f32 v[76:77], v[72:73], s[38:39] op_sel_hi:[1,0]
	v_exp_f32_e32 v78, v78
	v_exp_f32_e32 v76, v76
	v_exp_f32_e32 v77, v77
	v_exp_f32_e32 v79, v79
	v_pk_mul_f32 v[64:65], v[64:65], v[150:151] op_sel_hi:[1,0]
	v_pk_mul_f32 v[66:67], v[66:67], v[150:151] op_sel_hi:[1,0]
	v_pk_add_f32 v[76:77], v[76:77], 1.0 op_sel_hi:[1,0]
	v_pk_add_f32 v[78:79], v[78:79], 1.0 op_sel_hi:[1,0]
	v_rcp_f32_e32 v76, v76
	v_rcp_f32_e32 v77, v77
	v_rcp_f32_e32 v78, v78
	v_rcp_f32_e32 v79, v79
	v_pk_mul_f32 v[72:73], v[72:73], v[76:77]
	s_nop 0
	v_pk_mul_f32 v[72:73], v[64:65], v[72:73]
	v_pk_mul_f32 v[64:65], v[74:75], v[78:79]
	s_nop 0
	v_pk_mul_f32 v[74:75], v[66:67], v[64:65]
	v_cvt_pk_bf16_f32 v64, v68, v69
	v_cvt_pk_bf16_f32 v65, v70, v71
	v_cvt_pk_bf16_f32 v66, v72, v73
	s_nop 0
	v_cvt_pk_bf16_f32 v67, v74, v75
	global_store_dwordx4 v[84:85], v[64:67], off offset:2048 nt
	v_pk_mul_f32 v[60:61], v[60:61], v[148:149] op_sel_hi:[1,0]
	v_pk_mul_f32 v[62:63], v[62:63], v[148:149] op_sel_hi:[1,0]
	v_pk_mul_f32 v[66:67], v[60:61], s[38:39] op_sel_hi:[1,0]
	v_pk_mul_f32 v[68:69], v[62:63], s[38:39] op_sel_hi:[1,0]
	v_exp_f32_e32 v66, v66
	v_exp_f32_e32 v67, v67
	v_exp_f32_e32 v68, v68
	v_exp_f32_e32 v69, v69
	v_pk_mul_f32 v[52:53], v[52:53], v[148:149] op_sel_hi:[1,0]
	v_pk_add_f32 v[66:67], v[66:67], 1.0 op_sel_hi:[1,0]
	v_pk_mul_f32 v[54:55], v[54:55], v[148:149] op_sel_hi:[1,0]
	v_rcp_f32_e32 v66, v66
	v_rcp_f32_e32 v67, v67
	v_pk_add_f32 v[68:69], v[68:69], 1.0 op_sel_hi:[1,0]
	v_pk_mul_f32 v[56:57], v[56:57], v[148:149] op_sel_hi:[1,0]
	v_rcp_f32_e32 v68, v68
	v_rcp_f32_e32 v69, v69
	v_pk_mul_f32 v[60:61], v[60:61], v[66:67]
	v_pk_mul_f32 v[58:59], v[58:59], v[148:149] op_sel_hi:[1,0]
	v_pk_mul_f32 v[52:53], v[52:53], v[60:61]
	v_pk_mul_f32 v[60:61], v[62:63], v[68:69]
	v_pk_mul_f32 v[62:63], v[58:59], s[38:39] op_sel_hi:[1,0]
	v_pk_mul_f32 v[54:55], v[54:55], v[60:61]
	v_pk_mul_f32 v[60:61], v[56:57], s[38:39] op_sel_hi:[1,0]
	v_exp_f32_e32 v62, v62
	v_exp_f32_e32 v60, v60
	v_exp_f32_e32 v61, v61
	v_exp_f32_e32 v63, v63
	v_lshrrev_b32_e32 v64, 8, v151
	v_pk_mul_f32 v[48:49], v[48:49], v[148:149] op_sel_hi:[1,0]
	v_pk_add_f32 v[60:61], v[60:61], 1.0 op_sel_hi:[1,0]
	v_pk_add_f32 v[62:63], v[62:63], 1.0 op_sel_hi:[1,0]
	v_rcp_f32_e32 v60, v60
	v_rcp_f32_e32 v61, v61
	v_rcp_f32_e32 v62, v62
	v_rcp_f32_e32 v63, v63
	v_mul_hi_i32_i24_e32 v65, 0x2c0000, v64
	v_pk_mul_f32 v[56:57], v[56:57], v[60:61]
	v_mul_i32_i24_e32 v64, 0x2c0000, v64
	v_pk_mul_f32 v[56:57], v[48:49], v[56:57]
	v_pk_mul_f32 v[48:49], v[58:59], v[62:63]
; __device__ __forceinline__ unsigned pk2(float lo, float hi) { unsigned r; asm volatile("v_cvt_pk_bf16_f32 %0, %1, %2" : "=v"(r) : "v"(lo), "v"(hi)); return r; }
; #define PG8_BAR __builtin_amdgcn_s_barrier()
; template <class Epi>
; __device__ __forceinline__ void gemm_phase(LAS unsigned char* lds, const Gemm g, const StaticOrder& S, const Epi& E) {
;     ...
;         if (!has_next) break;
; #pragma unroll
;         for (int a = 0; a < 2; ++a)
; #pragma unroll
;             for (int b = 0; b < 2; ++b)
; #pragma unroll
;                 for (int m = 0; m < 4; ++m)
; #pragma unroll
;                     for (int n = 0; n < 2; ++n) acc[a][b][m][n] = (f32x4){0.f, 0.f, 0.f, 0.f};
;         cur = nxt; cA = nA; cB = nB; ++ui;
;         if (wr == 1) PG8_BAR;
;     __device__ __forceinline__ void operator()(const f32x4 (&acc)[2][2][4][2], const Unit& u, int wr, int wc, int fr, int fq) const {
;     ...
; #pragma unroll
;         for (int ai = 0; ai < 2; ++ai)
; #pragma unroll
;             for (int m = 0; m < 4; ++m) {
;                 const int row = row0 + ai * HALF + m * 16;
;                 const float rs = rsv[ai * 4 + m];
;                 const f32x4 g0 = acc[ai][0][m][0], g1 = acc[ai][0][m][1], u0 = acc[ai][1][m][0], u1 = acc[ai][1][m][1];
;                 const f32x2 o0 = swiglu_pk((f32x2){g0[0], g0[1]}, (f32x2){u0[0], u0[1]}, rs), o1 = swiglu_pk((f32x2){g0[2], g0[3]}, (f32x2){u0[2], u0[3]}, rs);
;                 const f32x2 o2 = swiglu_pk((f32x2){g1[0], g1[1]}, (f32x2){u1[0], u1[1]}, rs), o3 = swiglu_pk((f32x2){g1[2], g1[3]}, (f32x2){u1[2], u1[3]}, rs);
;                 u32x4 w; w.x = pk2(o0.x, o0.y); w.y = pk2(o1.x, o1.y); w.z = pk2(o2.x, o2.y); w.w = pk2(o3.x, o3.y);
;                 __builtin_nontemporal_store(w, (u32x4*)(G + (size_t)(row >> 8) * ((size_t)BM * FF) + (size_t)(col0 >> 6) * (BM * BK) + (size_t)(row & 255) * BK + (col0 & 63)));
;                 __builtin_amdgcn_sched_barrier(0);
;             }
	v_pk_mul_f32 v[50:51], v[50:51], v[148:149] op_sel_hi:[1,0]
	s_nop 0
	v_pk_mul_f32 v[58:59], v[50:51], v[48:49]
	v_cvt_pk_bf16_f32 v48, v52, v53
	v_cvt_pk_bf16_f32 v49, v54, v55
	v_lshl_add_u64 v[52:53], s[30:31], 0, v[64:65]
	v_lshlrev_b32_e32 v54, 7, v151
	v_lshl_add_u64 v[52:53], v[52:53], 0, s[6:7]
	v_and_b32_e32 v132, 0x6780, v54
	v_lshl_add_u64 v[52:53], v[52:53], 0, v[132:133]
	v_lshl_add_u64 v[52:53], v[52:53], 0, v[140:141]
	v_cvt_pk_bf16_f32 v50, v56, v57
	v_cvt_pk_bf16_f32 v51, v58, v59
	global_store_dwordx4 v[52:53], v[48:51], off nt
	v_pk_mul_f32 v[44:45], v[44:45], v[146:147] op_sel_hi:[1,0]
	v_pk_mul_f32 v[46:47], v[46:47], v[146:147] op_sel_hi:[1,0]
	v_pk_mul_f32 v[48:49], v[44:45], s[38:39] op_sel_hi:[1,0]
	v_pk_mul_f32 v[50:51], v[46:47], s[38:39] op_sel_hi:[1,0]
	v_exp_f32_e32 v48, v48
	v_exp_f32_e32 v49, v49
	v_exp_f32_e32 v50, v50
	v_exp_f32_e32 v51, v51
	v_pk_mul_f32 v[36:37], v[36:37], v[146:147] op_sel_hi:[1,0]
	v_pk_add_f32 v[48:49], v[48:49], 1.0 op_sel_hi:[1,0]
	v_pk_mul_f32 v[38:39], v[38:39], v[146:147] op_sel_hi:[1,0]
	v_rcp_f32_e32 v48, v48
	v_rcp_f32_e32 v49, v49
	v_pk_add_f32 v[50:51], v[50:51], 1.0 op_sel_hi:[1,0]
	v_pk_mul_f32 v[40:41], v[40:41], v[146:147] op_sel_hi:[1,0]
	v_rcp_f32_e32 v50, v50
	v_rcp_f32_e32 v51, v51
	v_pk_mul_f32 v[44:45], v[44:45], v[48:49]
	v_pk_mul_f32 v[42:43], v[42:43], v[146:147] op_sel_hi:[1,0]
	v_pk_mul_f32 v[36:37], v[36:37], v[44:45]
	v_pk_mul_f32 v[44:45], v[46:47], v[50:51]
	v_pk_mul_f32 v[46:47], v[42:43], s[38:39] op_sel_hi:[1,0]
	v_pk_mul_f32 v[38:39], v[38:39], v[44:45]
	v_pk_mul_f32 v[44:45], v[40:41], s[38:39] op_sel_hi:[1,0]
	v_exp_f32_e32 v46, v46
	v_exp_f32_e32 v44, v44
	v_exp_f32_e32 v45, v45
	v_exp_f32_e32 v47, v47
	v_pk_mul_f32 v[32:33], v[32:33], v[146:147] op_sel_hi:[1,0]
	v_pk_mul_f32 v[34:35], v[34:35], v[146:147] op_sel_hi:[1,0]
	v_pk_add_f32 v[44:45], v[44:45], 1.0 op_sel_hi:[1,0]
	v_pk_add_f32 v[46:47], v[46:47], 1.0 op_sel_hi:[1,0]
	v_rcp_f32_e32 v44, v44
	v_rcp_f32_e32 v45, v45
	v_rcp_f32_e32 v46, v46
	v_rcp_f32_e32 v47, v47
	v_pk_mul_f32 v[40:41], v[40:41], v[44:45]
	s_nop 0
	v_pk_mul_f32 v[40:41], v[32:33], v[40:41]
	v_pk_mul_f32 v[32:33], v[42:43], v[46:47]
	s_nop 0
	v_pk_mul_f32 v[42:43], v[34:35], v[32:33]
	v_cvt_pk_bf16_f32 v32, v36, v37
	v_cvt_pk_bf16_f32 v33, v38, v39
	v_cvt_pk_bf16_f32 v34, v40, v41
	s_nop 0
	v_cvt_pk_bf16_f32 v35, v42, v43
	global_store_dwordx4 v[52:53], v[32:35], off offset:2048 nt
	v_pk_mul_f32 v[28:29], v[28:29], v[144:145] op_sel_hi:[1,0]
	v_pk_mul_f32 v[30:31], v[30:31], v[144:145] op_sel_hi:[1,0]
	v_pk_mul_f32 v[32:33], v[28:29], s[38:39] op_sel_hi:[1,0]
	v_pk_mul_f32 v[34:35], v[30:31], s[38:39] op_sel_hi:[1,0]
	v_exp_f32_e32 v32, v32
	v_exp_f32_e32 v33, v33
	v_exp_f32_e32 v34, v34
	v_exp_f32_e32 v35, v35
	v_pk_mul_f32 v[20:21], v[20:21], v[144:145] op_sel_hi:[1,0]
	v_pk_add_f32 v[32:33], v[32:33], 1.0 op_sel_hi:[1,0]
	v_pk_mul_f32 v[22:23], v[22:23], v[144:145] op_sel_hi:[1,0]
	v_rcp_f32_e32 v32, v32
	v_rcp_f32_e32 v33, v33
	v_pk_add_f32 v[34:35], v[34:35], 1.0 op_sel_hi:[1,0]
	v_pk_mul_f32 v[24:25], v[24:25], v[144:145] op_sel_hi:[1,0]
	v_rcp_f32_e32 v34, v34
	v_rcp_f32_e32 v35, v35
	v_pk_mul_f32 v[28:29], v[28:29], v[32:33]
	v_pk_mul_f32 v[26:27], v[26:27], v[144:145] op_sel_hi:[1,0]
	v_pk_mul_f32 v[20:21], v[20:21], v[28:29]
	v_pk_mul_f32 v[28:29], v[30:31], v[34:35]
	v_pk_mul_f32 v[30:31], v[26:27], s[38:39] op_sel_hi:[1,0]
	v_pk_mul_f32 v[22:23], v[22:23], v[28:29]
	v_pk_mul_f32 v[28:29], v[24:25], s[38:39] op_sel_hi:[1,0]
	v_exp_f32_e32 v30, v30
	v_exp_f32_e32 v28, v28
	v_exp_f32_e32 v29, v29
	v_exp_f32_e32 v31, v31
	v_pk_mul_f32 v[16:17], v[16:17], v[144:145] op_sel_hi:[1,0]
	v_pk_mul_f32 v[18:19], v[18:19], v[144:145] op_sel_hi:[1,0]
	v_pk_add_f32 v[28:29], v[28:29], 1.0 op_sel_hi:[1,0]
	v_pk_add_f32 v[30:31], v[30:31], 1.0 op_sel_hi:[1,0]
	v_rcp_f32_e32 v28, v28
	v_rcp_f32_e32 v29, v29
	v_rcp_f32_e32 v30, v30
	v_rcp_f32_e32 v31, v31
	v_pk_mul_f32 v[24:25], v[24:25], v[28:29]
	s_nop 0
	v_pk_mul_f32 v[24:25], v[16:17], v[24:25]
	v_pk_mul_f32 v[16:17], v[26:27], v[30:31]
	s_nop 0
	v_pk_mul_f32 v[26:27], v[18:19], v[16:17]
	v_cvt_pk_bf16_f32 v16, v20, v21
	v_add_co_u32_e32 v20, vcc, s59, v52
	v_cvt_pk_bf16_f32 v17, v22, v23
	v_cvt_pk_bf16_f32 v18, v24, v25
	v_cvt_pk_bf16_f32 v19, v26, v27
	s_nop 1
	v_addc_co_u32_e32 v21, vcc, 0, v53, vcc
	global_store_dwordx4 v[20:21], v[16:19], off nt
	v_pk_mul_f32 v[12:13], v[12:13], v[142:143] op_sel_hi:[1,0]
	v_pk_mul_f32 v[14:15], v[14:15], v[142:143] op_sel_hi:[1,0]
	v_pk_mul_f32 v[16:17], v[12:13], s[38:39] op_sel_hi:[1,0]
	v_pk_mul_f32 v[18:19], v[14:15], s[38:39] op_sel_hi:[1,0]
	v_exp_f32_e32 v16, v16
	v_exp_f32_e32 v17, v17
	v_exp_f32_e32 v18, v18
	v_exp_f32_e32 v19, v19
	v_pk_mul_f32 v[4:5], v[4:5], v[142:143] op_sel_hi:[1,0]
	v_pk_add_f32 v[16:17], v[16:17], 1.0 op_sel_hi:[1,0]
	v_pk_mul_f32 v[6:7], v[6:7], v[142:143] op_sel_hi:[1,0]
	v_rcp_f32_e32 v16, v16
	v_rcp_f32_e32 v17, v17
	v_pk_add_f32 v[18:19], v[18:19], 1.0 op_sel_hi:[1,0]
	v_pk_mul_f32 v[8:9], v[8:9], v[142:143] op_sel_hi:[1,0]
	v_rcp_f32_e32 v18, v18
	v_rcp_f32_e32 v19, v19
	v_pk_mul_f32 v[12:13], v[12:13], v[16:17]
	v_pk_mul_f32 v[10:11], v[10:11], v[142:143] op_sel_hi:[1,0]
	v_pk_mul_f32 v[4:5], v[4:5], v[12:13]
	v_pk_mul_f32 v[12:13], v[14:15], v[18:19]
	v_pk_mul_f32 v[14:15], v[10:11], s[38:39] op_sel_hi:[1,0]
	v_pk_mul_f32 v[6:7], v[6:7], v[12:13]
	v_pk_mul_f32 v[12:13], v[8:9], s[38:39] op_sel_hi:[1,0]
	v_exp_f32_e32 v14, v14
	v_exp_f32_e32 v12, v12
	v_exp_f32_e32 v13, v13
	v_exp_f32_e32 v15, v15
	v_pk_mul_f32 v[0:1], v[0:1], v[142:143] op_sel_hi:[1,0]
	v_pk_mul_f32 v[2:3], v[2:3], v[142:143] op_sel_hi:[1,0]
	v_pk_add_f32 v[12:13], v[12:13], 1.0 op_sel_hi:[1,0]
	v_pk_add_f32 v[14:15], v[14:15], 1.0 op_sel_hi:[1,0]
	v_rcp_f32_e32 v12, v12
	v_rcp_f32_e32 v13, v13
	v_rcp_f32_e32 v14, v14
	v_rcp_f32_e32 v15, v15
	v_pk_mul_f32 v[8:9], v[8:9], v[12:13]
	s_nop 0
	v_pk_mul_f32 v[8:9], v[0:1], v[8:9]
	v_pk_mul_f32 v[0:1], v[10:11], v[14:15]
	s_nop 0
	v_pk_mul_f32 v[10:11], v[2:3], v[0:1]
	v_cvt_pk_bf16_f32 v0, v4, v5
	v_cvt_pk_bf16_f32 v1, v6, v7
	v_cvt_pk_bf16_f32 v2, v8, v9
	s_nop 0
	v_cvt_pk_bf16_f32 v3, v10, v11
	global_store_dwordx4 v[20:21], v[0:3], off offset:2048 nt
	s_and_b64 vcc, exec, s[4:5]
	s_mov_b64 s[4:5], -1
	s_cbranch_vccnz .LBB0_103
	s_andn2_b64 vcc, exec, s[22:23]
	s_cbranch_vccnz .LBB0_102
	s_barrier
	s_branch .LBB0_102

; #define PG8_STAGE(bufoff, gbase, voff) do { const char* _gb = (const char*)(gbase); asm volatile("" : "+s"(_gb));     \
;         _Pragma("unroll") for (int _i = 0; _i < 2; ++_i) \
;         __builtin_amdgcn_global_load_lds((const unsigned*)(_gb + (voff)[_i]), (LAS unsigned*)(lds + (bufoff) + ldsw + _i * 8192), 16, 0, 0); } while (0)
; #define PG8_VOFF_OPAQUE asm volatile("" : "+v"(voffA[0]), "+v"(voffA[1]), "+v"(voffB[0]), "+v"(voffB[1]))
; #define PG8_LDA(dst, b, h) do { _Pragma("unroll") for (int m = 0; m < 4; ++m) _Pragma("unroll") for (int k = 0; k < 2; ++k) dst[m][k] = *(const LAS bf16x8*)(lds + PG8_SA(b, h) + aoff + m * 2048 + k * 1024); } while (0)
; #define PG8_LDB(dst, b, h) do { _Pragma("unroll") for (int n = 0; n < 2; ++n) _Pragma("unroll") for (int k = 0; k < 2; ++k) dst[n][k] = *(const LAS bf16x8*)(lds + PG8_SB(b, h) + boff + n * 2048 + k * 1024); } while (0)
; #define PG8_SCHED __builtin_amdgcn_sched_barrier(0)
; template <class Epi>
; __device__ __forceinline__ void gemm_phase(LAS unsigned char* lds, const Gemm g, const StaticOrder& S, const Epi& E) {
;     ...
;         const bool has_next = S.next(ui + 1, nxt);
;         const char* nA = has_next ? (const char*)gA + (size_t)nxt.pm * tstepA + (size_t)nxt.pn * acolb + (size_t)nxt.kofs * kstepA : cA; const char* nB = has_next ? (const char*)gB + (size_t)nxt.pn * tstepB + (size_t)nxt.kofs * kstepB : cB;
;         const int nt = cur.nt;
;         for (int t = 0; t < nt; t += 2) {
;             PG8_VOFF_OPAQUE;
;             const bool last = (t == nt - 2);
;             const char* a1 = cA + (size_t)(t + 1) * kstepA;
;             const char* a2 = last ? nA : cA + (size_t)(t + 2) * kstepA; const char* b2 = last ? nB : cB + (size_t)(t + 2) * kstepB;
;             const char* a3 = a2 + kstepA; const char* b3 = b2 + kstepB;
;             PG8_LDB(B0, 0, 0); PG8_LDB(B1, 0, 1); PG8_SCHED; PG8_LDA(At, 0, 0); PG8_STAGE(PG8_SA(1, 1), a1 + hstepA, voffA);
;     ...
;         for (int a = 0; a < 2; ++a)
; #pragma unroll
;             for (int b = 0; b < 2; ++b)
; #pragma unroll
;                 for (int m = 0; m < 4; ++m)
; #pragma unroll
;                     for (int n = 0; n < 2; ++n) acc[a][b][m][n] = (f32x4){0.f, 0.f, 0.f, 0.f};
;         cur = nxt; cA = nA; cB = nB; ++ui;
.LBB0_1206:
	s_ashr_i32 s45, s44, 31
	s_lshl_b64 s[48:49], s[44:45], 20
	s_add_u32 s48, s12, s48
	s_addc_u32 s49, s13, s49
	s_and_b64 s[10:11], s[10:11], exec
	s_cselect_b32 s45, s49, s55
	s_cselect_b32 s64, s48, s54
	s_add_u32 s65, s52, 0x100
	s_addc_u32 s66, s53, 0
	s_add_u32 s67, s54, 0x100
	v_mov_b32_e32 v0, 0
	s_addc_u32 s68, s55, 0
	s_mov_b32 s69, -2
	v_mov_b32_e32 v1, v0
	v_mov_b32_e32 v2, v0
	v_mov_b32_e32 v3, v0
	v_mov_b32_e32 v4, v0
	v_mov_b32_e32 v5, v0
	v_mov_b32_e32 v6, v0
	v_mov_b32_e32 v7, v0
	v_mov_b32_e32 v16, v0
	v_mov_b32_e32 v17, v0
	v_mov_b32_e32 v18, v0
	v_mov_b32_e32 v19, v0
	v_mov_b32_e32 v20, v0
	v_mov_b32_e32 v21, v0
	v_mov_b32_e32 v22, v0
	v_mov_b32_e32 v23, v0
	v_mov_b32_e32 v32, v0
	v_mov_b32_e32 v33, v0
	v_mov_b32_e32 v34, v0
	v_mov_b32_e32 v35, v0
	v_mov_b32_e32 v36, v0
	v_mov_b32_e32 v37, v0
	v_mov_b32_e32 v38, v0
	v_mov_b32_e32 v39, v0
	v_mov_b32_e32 v48, v0
	v_mov_b32_e32 v49, v0
	v_mov_b32_e32 v50, v0
	v_mov_b32_e32 v51, v0
	v_mov_b32_e32 v52, v0
	v_mov_b32_e32 v53, v0
	v_mov_b32_e32 v54, v0
	v_mov_b32_e32 v55, v0
	v_mov_b32_e32 v8, v0
	v_mov_b32_e32 v9, v0
	v_mov_b32_e32 v10, v0
	v_mov_b32_e32 v11, v0
	v_mov_b32_e32 v12, v0
	v_mov_b32_e32 v13, v0
	v_mov_b32_e32 v14, v0
	v_mov_b32_e32 v15, v0
	v_mov_b32_e32 v24, v0
	v_mov_b32_e32 v25, v0
	v_mov_b32_e32 v26, v0
	v_mov_b32_e32 v27, v0
	v_mov_b32_e32 v28, v0
	v_mov_b32_e32 v29, v0
	v_mov_b32_e32 v30, v0
	v_mov_b32_e32 v31, v0
	v_mov_b32_e32 v40, v0
	v_mov_b32_e32 v41, v0
	v_mov_b32_e32 v42, v0
	v_mov_b32_e32 v43, v0
	v_mov_b32_e32 v44, v0
	v_mov_b32_e32 v45, v0
	v_mov_b32_e32 v46, v0
	v_mov_b32_e32 v47, v0
	v_mov_b32_e32 v56, v0
	v_mov_b32_e32 v57, v0
	v_mov_b32_e32 v58, v0
	v_mov_b32_e32 v59, v0
	v_mov_b32_e32 v60, v0
	v_mov_b32_e32 v61, v0
	v_mov_b32_e32 v62, v0
	v_mov_b32_e32 v63, v0
	v_mov_b32_e32 v64, v0
	v_mov_b32_e32 v65, v0
	v_mov_b32_e32 v66, v0
	v_mov_b32_e32 v67, v0
	v_mov_b32_e32 v68, v0
	v_mov_b32_e32 v69, v0
	v_mov_b32_e32 v70, v0
	v_mov_b32_e32 v71, v0
	v_mov_b32_e32 v80, v0
	v_mov_b32_e32 v81, v0
	v_mov_b32_e32 v82, v0
	v_mov_b32_e32 v83, v0
	v_mov_b32_e32 v84, v0
	v_mov_b32_e32 v85, v0
	v_mov_b32_e32 v86, v0
	v_mov_b32_e32 v87, v0
	v_mov_b32_e32 v96, v0
	v_mov_b32_e32 v97, v0
	v_mov_b32_e32 v98, v0
	v_mov_b32_e32 v99, v0
	v_mov_b32_e32 v100, v0
	v_mov_b32_e32 v101, v0
	v_mov_b32_e32 v102, v0
	v_mov_b32_e32 v103, v0
	v_mov_b32_e32 v112, v0
	v_mov_b32_e32 v113, v0
	v_mov_b32_e32 v114, v0
	v_mov_b32_e32 v115, v0
	v_mov_b32_e32 v116, v0
	v_mov_b32_e32 v117, v0
	v_mov_b32_e32 v118, v0
	v_mov_b32_e32 v119, v0
	v_mov_b32_e32 v72, v0
	v_mov_b32_e32 v73, v0
	v_mov_b32_e32 v74, v0
	v_mov_b32_e32 v75, v0
	v_mov_b32_e32 v76, v0
	v_mov_b32_e32 v77, v0
	v_mov_b32_e32 v78, v0
	v_mov_b32_e32 v79, v0
	v_mov_b32_e32 v88, v0
	v_mov_b32_e32 v89, v0
	v_mov_b32_e32 v90, v0
	v_mov_b32_e32 v91, v0
	v_mov_b32_e32 v92, v0
	v_mov_b32_e32 v93, v0
	v_mov_b32_e32 v94, v0
	v_mov_b32_e32 v95, v0
	v_mov_b32_e32 v104, v0
	v_mov_b32_e32 v105, v0
	v_mov_b32_e32 v106, v0
	v_mov_b32_e32 v107, v0
	v_mov_b32_e32 v108, v0
	v_mov_b32_e32 v109, v0
	v_mov_b32_e32 v110, v0
	v_mov_b32_e32 v111, v0
	v_mov_b32_e32 v120, v0
	v_mov_b32_e32 v121, v0
	v_mov_b32_e32 v122, v0
	v_mov_b32_e32 v123, v0
	v_mov_b32_e32 v124, v0
	v_mov_b32_e32 v125, v0
	v_mov_b32_e32 v126, v0
	v_mov_b32_e32 v127, v0
.LBB0_1207:
	ds_read_b128 v[150:153], v135
	ds_read_b128 v[154:157], v135 offset:1024
	ds_read_b128 v[158:161], v135 offset:2048
	ds_read_b128 v[162:165], v135 offset:3072
	ds_read_b128 v[166:169], v143
	ds_read_b128 v[170:173], v143 offset:1024
	ds_read_b128 v[174:177], v143 offset:2048
	ds_read_b128 v[178:181], v143 offset:3072
	s_cmp_eq_u32 s69, 28
	s_cselect_b32 s54, s64, s67
	s_cselect_b32 s55, s45, s68
	s_cselect_b32 s52, s46, s65
	s_cselect_b32 s53, s47, s66
	s_add_u32 s10, s67, 0xffffff80
	s_addc_u32 s11, s68, -1
	s_add_u32 s56, s67, s22
	s_addc_u32 s57, s68, s23
	s_add_u32 s56, s56, 0xffffff80
	s_addc_u32 s57, s57, -1
	s_mov_b32 m0, s33
	ds_read_b128 v[182:185], v145
	ds_read_b128 v[186:189], v145 offset:1024
	ds_read_b128 v[190:193], v145 offset:2048
	ds_read_b128 v[194:197], v145 offset:3072
	ds_read_b128 v[198:201], v145 offset:4096
	ds_read_b128 v[202:205], v145 offset:5120
	ds_read_b128 v[206:209], v145 offset:6144
	ds_read_b128 v[210:213], v145 offset:7168
	s_nop 0
	global_load_lds_dwordx4 v134, s[10:11]
	s_mov_b32 m0, s43
	s_nop 0
	global_load_lds_dwordx4 v130, s[10:11]
	s_add_i32 m0, s6, 0xc000
	s_nop 0
	global_load_lds_dwordx4 v134, s[56:57]
	s_add_i32 m0, s6, 0xe000
	s_nop 0
	global_load_lds_dwordx4 v130, s[56:57]
	s_waitcnt vmcnt(8)
	s_waitcnt lgkmcnt(0)
	s_barrier
; #define PG8_STAGE(bufoff, gbase, voff) do { const char* _gb = (const char*)(gbase); asm volatile("" : "+s"(_gb));     \
;         _Pragma("unroll") for (int _i = 0; _i < 2; ++_i) \
;         __builtin_amdgcn_global_load_lds((const unsigned*)(_gb + (voff)[_i]), (LAS unsigned*)(lds + (bufoff) + ldsw + _i * 8192), 16, 0, 0); } while (0)
; #define PG8_LDA(dst, b, h) do { _Pragma("unroll") for (int m = 0; m < 4; ++m) _Pragma("unroll") for (int k = 0; k < 2; ++k) dst[m][k] = *(const LAS bf16x8*)(lds + PG8_SA(b, h) + aoff + m * 2048 + k * 1024); } while (0)
; #define PG8_WAIT_V(n) asm volatile("s_waitcnt vmcnt(" #n ")" ::: "memory")
; #define PG8_WAIT_L(n) asm volatile("s_waitcnt lgkmcnt(" #n ")" ::: "memory")
; #define PG8_BAR __builtin_amdgcn_s_barrier()
; #define PG8_SCHED __builtin_amdgcn_sched_barrier(0)
; template <class Epi>
; __device__ __forceinline__ void gemm_phase(LAS unsigned char* lds, const Gemm g, const StaticOrder& S, const Epi& E) {
;     ...
;             PG8_WAIT_V(8); PG8_WAIT_L(0); PG8_BAR; PG8_MMA2(0, At, B0, B1); PG8_BAR; PG8_SCHED;
;             PG8_LDA(At, 0, 1); PG8_STAGE(PG8_SB(0, 0), b2, voffB); PG8_STAGE(PG8_SB(0, 1), b2 + hstepB, voffB); PG8_STAGE(PG8_SA(0, 0), a2, voffA);
;             PG8_WAIT_V(8); PG8_WAIT_L(0); PG8_BAR; PG8_MMA2(1, At, B0, B1); PG8_BAR; PG8_SCHED;
	s_setprio 1
	s_waitcnt lgkmcnt(0)
	v_mfma_f32_16x16x32_bf16 v[124:127], v[150:153], v[182:185], v[124:127]
	v_mfma_f32_16x16x32_bf16 v[120:123], v[158:161], v[182:185], v[120:123]
	v_mfma_f32_16x16x32_bf16 v[108:111], v[150:153], v[190:193], v[108:111]
	v_mfma_f32_16x16x32_bf16 v[104:107], v[158:161], v[190:193], v[104:107]
	v_mfma_f32_16x16x32_bf16 v[92:95], v[150:153], v[198:201], v[92:95]
	v_mfma_f32_16x16x32_bf16 v[88:91], v[158:161], v[198:201], v[88:91]
	v_mfma_f32_16x16x32_bf16 v[76:79], v[150:153], v[206:209], v[76:79]
	v_mfma_f32_16x16x32_bf16 v[72:75], v[158:161], v[206:209], v[72:75]
	v_mfma_f32_16x16x32_bf16 v[116:119], v[166:169], v[182:185], v[116:119]
	v_mfma_f32_16x16x32_bf16 v[112:115], v[174:177], v[182:185], v[112:115]
	v_mfma_f32_16x16x32_bf16 v[100:103], v[166:169], v[190:193], v[100:103]
	v_mfma_f32_16x16x32_bf16 v[96:99], v[174:177], v[190:193], v[96:99]
	v_mfma_f32_16x16x32_bf16 v[84:87], v[166:169], v[198:201], v[84:87]
	v_mfma_f32_16x16x32_bf16 v[80:83], v[174:177], v[198:201], v[80:83]
	v_mfma_f32_16x16x32_bf16 v[68:71], v[166:169], v[206:209], v[68:71]
	v_mfma_f32_16x16x32_bf16 v[64:67], v[174:177], v[206:209], v[64:67]
	v_mfma_f32_16x16x32_bf16 v[124:127], v[154:157], v[186:189], v[124:127]
	v_mfma_f32_16x16x32_bf16 v[120:123], v[162:165], v[186:189], v[120:123]
	v_mfma_f32_16x16x32_bf16 v[108:111], v[154:157], v[194:197], v[108:111]
	v_mfma_f32_16x16x32_bf16 v[104:107], v[162:165], v[194:197], v[104:107]
	v_mfma_f32_16x16x32_bf16 v[92:95], v[154:157], v[202:205], v[92:95]
	v_mfma_f32_16x16x32_bf16 v[88:91], v[162:165], v[202:205], v[88:91]
	v_mfma_f32_16x16x32_bf16 v[76:79], v[154:157], v[210:213], v[76:79]
	v_mfma_f32_16x16x32_bf16 v[72:75], v[162:165], v[210:213], v[72:75]
	v_mfma_f32_16x16x32_bf16 v[116:119], v[170:173], v[186:189], v[116:119]
	v_mfma_f32_16x16x32_bf16 v[112:115], v[178:181], v[186:189], v[112:115]
	v_mfma_f32_16x16x32_bf16 v[100:103], v[170:173], v[194:197], v[100:103]
	v_mfma_f32_16x16x32_bf16 v[96:99], v[178:181], v[194:197], v[96:99]
	v_mfma_f32_16x16x32_bf16 v[84:87], v[170:173], v[202:205], v[84:87]
	v_mfma_f32_16x16x32_bf16 v[80:83], v[178:181], v[202:205], v[80:83]
	v_mfma_f32_16x16x32_bf16 v[68:71], v[170:173], v[210:213], v[68:71]
	v_mfma_f32_16x16x32_bf16 v[64:67], v[178:181], v[210:213], v[64:67]
	s_setprio 0
	s_barrier
	s_add_i32 s70, s59, s3
	s_mov_b64 s[56:57], s[52:53]
	s_mov_b32 m0, s70
	ds_read_b128 v[182:185], v145 offset:16384
	ds_read_b128 v[186:189], v145 offset:17408
	ds_read_b128 v[190:193], v145 offset:18432
	ds_read_b128 v[194:197], v145 offset:19456
	ds_read_b128 v[198:201], v145 offset:20480
	ds_read_b128 v[202:205], v145 offset:21504
	ds_read_b128 v[206:209], v145 offset:22528
	ds_read_b128 v[210:213], v145 offset:23552
	s_nop 0
	global_load_lds_dwordx4 v149, s[56:57]
	s_add_i32 m0, s70, 0x2000
	s_nop 0
	global_load_lds_dwordx4 v128, s[56:57]
	s_add_u32 s56, s52, s16
	s_addc_u32 s57, s53, s17
	s_add_i32 s72, s60, s3
	s_mov_b64 s[70:71], s[56:57]
	s_mov_b32 m0, s72
	s_nop 0
	global_load_lds_dwordx4 v149, s[70:71]
	s_add_i32 m0, s72, 0x2000
	s_nop 0
	global_load_lds_dwordx4 v128, s[70:71]
	s_waitcnt vmcnt(6)
	s_waitcnt lgkmcnt(0)
	s_barrier
	s_setprio 1
	s_waitcnt lgkmcnt(0)
	v_mfma_f32_16x16x32_bf16 v[60:63], v[150:153], v[182:185], v[60:63]
	v_mfma_f32_16x16x32_bf16 v[56:59], v[158:161], v[182:185], v[56:59]
	v_mfma_f32_16x16x32_bf16 v[44:47], v[150:153], v[190:193], v[44:47]
	v_mfma_f32_16x16x32_bf16 v[40:43], v[158:161], v[190:193], v[40:43]
	v_mfma_f32_16x16x32_bf16 v[28:31], v[150:153], v[198:201], v[28:31]
	v_mfma_f32_16x16x32_bf16 v[24:27], v[158:161], v[198:201], v[24:27]
	v_mfma_f32_16x16x32_bf16 v[12:15], v[150:153], v[206:209], v[12:15]
	v_mfma_f32_16x16x32_bf16 v[8:11], v[158:161], v[206:209], v[8:11]
	v_mfma_f32_16x16x32_bf16 v[52:55], v[166:169], v[182:185], v[52:55]
	v_mfma_f32_16x16x32_bf16 v[48:51], v[174:177], v[182:185], v[48:51]
	v_mfma_f32_16x16x32_bf16 v[36:39], v[166:169], v[190:193], v[36:39]
	v_mfma_f32_16x16x32_bf16 v[32:35], v[174:177], v[190:193], v[32:35]
	v_mfma_f32_16x16x32_bf16 v[20:23], v[166:169], v[198:201], v[20:23]
	v_mfma_f32_16x16x32_bf16 v[16:19], v[174:177], v[198:201], v[16:19]
	v_mfma_f32_16x16x32_bf16 v[4:7], v[166:169], v[206:209], v[4:7]
	v_mfma_f32_16x16x32_bf16 v[0:3], v[174:177], v[206:209], v[0:3]
	v_mfma_f32_16x16x32_bf16 v[60:63], v[154:157], v[186:189], v[60:63]
	v_mfma_f32_16x16x32_bf16 v[56:59], v[162:165], v[186:189], v[56:59]
	v_mfma_f32_16x16x32_bf16 v[44:47], v[154:157], v[194:197], v[44:47]
	v_mfma_f32_16x16x32_bf16 v[40:43], v[162:165], v[194:197], v[40:43]
	v_mfma_f32_16x16x32_bf16 v[28:31], v[154:157], v[202:205], v[28:31]
	v_mfma_f32_16x16x32_bf16 v[24:27], v[162:165], v[202:205], v[24:27]
	v_mfma_f32_16x16x32_bf16 v[12:15], v[154:157], v[210:213], v[12:15]
	v_mfma_f32_16x16x32_bf16 v[8:11], v[162:165], v[210:213], v[8:11]
	v_mfma_f32_16x16x32_bf16 v[52:55], v[170:173], v[186:189], v[52:55]
	v_mfma_f32_16x16x32_bf16 v[48:51], v[178:181], v[186:189], v[48:51]
	v_mfma_f32_16x16x32_bf16 v[36:39], v[170:173], v[194:197], v[36:39]
	v_mfma_f32_16x16x32_bf16 v[32:35], v[178:181], v[194:197], v[32:35]
	v_mfma_f32_16x16x32_bf16 v[20:23], v[170:173], v[202:205], v[20:23]
	v_mfma_f32_16x16x32_bf16 v[16:19], v[178:181], v[202:205], v[16:19]
	v_mfma_f32_16x16x32_bf16 v[4:7], v[170:173], v[210:213], v[4:7]
	v_mfma_f32_16x16x32_bf16 v[0:3], v[178:181], v[210:213], v[0:3]
	s_setprio 0
	s_barrier
; #define PG8_STAGE(bufoff, gbase, voff) do { const char* _gb = (const char*)(gbase); asm volatile("" : "+s"(_gb));     \
;         _Pragma("unroll") for (int _i = 0; _i < 2; ++_i) \
;         __builtin_amdgcn_global_load_lds((const unsigned*)(_gb + (voff)[_i]), (LAS unsigned*)(lds + (bufoff) + ldsw + _i * 8192), 16, 0, 0); } while (0)
; #define PG8_LDA(dst, b, h) do { _Pragma("unroll") for (int m = 0; m < 4; ++m) _Pragma("unroll") for (int k = 0; k < 2; ++k) dst[m][k] = *(const LAS bf16x8*)(lds + PG8_SA(b, h) + aoff + m * 2048 + k * 1024); } while (0)
; #define PG8_LDB(dst, b, h) do { _Pragma("unroll") for (int n = 0; n < 2; ++n) _Pragma("unroll") for (int k = 0; k < 2; ++k) dst[n][k] = *(const LAS bf16x8*)(lds + PG8_SB(b, h) + boff + n * 2048 + k * 1024); } while (0)
; #define PG8_WAIT_V(n) asm volatile("s_waitcnt vmcnt(" #n ")" ::: "memory")
; #define PG8_WAIT_L(n) asm volatile("s_waitcnt lgkmcnt(" #n ")" ::: "memory")
; #define PG8_BAR __builtin_amdgcn_s_barrier()
; #define PG8_SCHED __builtin_amdgcn_sched_barrier(0)
; template <class Epi>
; __device__ __forceinline__ void gemm_phase(LAS unsigned char* lds, const Gemm g, const StaticOrder& S, const Epi& E) {
;     ...
;             PG8_LDB(B0, 1, 0); PG8_LDB(B1, 1, 1); PG8_SCHED; PG8_LDA(At, 1, 0); PG8_STAGE(PG8_SA(0, 1), a2 + hstepA, voffA);
;             PG8_WAIT_V(8); PG8_WAIT_L(0); PG8_BAR; PG8_MMA2(0, At, B0, B1); PG8_BAR; PG8_SCHED;
;             PG8_LDA(At, 1, 1); PG8_STAGE(PG8_SB(1, 0), b3, voffB); PG8_STAGE(PG8_SB(1, 1), b3 + hstepB, voffB); PG8_STAGE(PG8_SA(1, 0), a3, voffA);
;             PG8_WAIT_V(8); PG8_WAIT_L(0); PG8_BAR; PG8_MMA2(1, At, B0, B1); PG8_BAR; PG8_SCHED;
;         }
;         if (wr == 0) PG8_BAR;
	s_add_i32 s70, 0, 0x18000
	v_add_u32_e32 v132, s70, v131
	s_add_i32 s71, 0, 0x1c000
	ds_read_b128 v[150:153], v132
	ds_read_b128 v[154:157], v132 offset:1024
	ds_read_b128 v[158:161], v132 offset:2048
	ds_read_b128 v[162:165], v132 offset:3072
	v_add_u32_e32 v132, s71, v131
	ds_read_b128 v[166:169], v132
	ds_read_b128 v[170:173], v132 offset:1024
	ds_read_b128 v[174:177], v132 offset:2048
	ds_read_b128 v[178:181], v132 offset:3072
	s_add_u32 s10, s54, s22
	s_addc_u32 s11, s55, s23
	s_mov_b32 m0, s6
	ds_read_b128 v[182:185], v145 offset:32768
	ds_read_b128 v[186:189], v145 offset:33792
	ds_read_b128 v[190:193], v145 offset:34816
	ds_read_b128 v[194:197], v145 offset:35840
	ds_read_b128 v[198:201], v145 offset:36864
	ds_read_b128 v[202:205], v145 offset:37888
	ds_read_b128 v[206:209], v145 offset:38912
	ds_read_b128 v[210:213], v145 offset:39936
	s_nop 0
	global_load_lds_dwordx4 v134, s[54:55]
	s_mov_b32 m0, s7
	s_nop 0
	global_load_lds_dwordx4 v130, s[54:55]
	s_mov_b32 m0, s18
	s_nop 0
	global_load_lds_dwordx4 v134, s[10:11]
	s_mov_b32 m0, s19
	s_nop 0
	global_load_lds_dwordx4 v130, s[10:11]
	s_waitcnt vmcnt(8)
	s_waitcnt lgkmcnt(0)
	s_barrier
	s_setprio 1
	s_waitcnt lgkmcnt(0)
	v_mfma_f32_16x16x32_bf16 v[124:127], v[150:153], v[182:185], v[124:127]
	v_mfma_f32_16x16x32_bf16 v[120:123], v[158:161], v[182:185], v[120:123]
	v_mfma_f32_16x16x32_bf16 v[108:111], v[150:153], v[190:193], v[108:111]
	v_mfma_f32_16x16x32_bf16 v[104:107], v[158:161], v[190:193], v[104:107]
	v_mfma_f32_16x16x32_bf16 v[92:95], v[150:153], v[198:201], v[92:95]
	v_mfma_f32_16x16x32_bf16 v[88:91], v[158:161], v[198:201], v[88:91]
	v_mfma_f32_16x16x32_bf16 v[76:79], v[150:153], v[206:209], v[76:79]
	v_mfma_f32_16x16x32_bf16 v[72:75], v[158:161], v[206:209], v[72:75]
	v_mfma_f32_16x16x32_bf16 v[116:119], v[166:169], v[182:185], v[116:119]
	v_mfma_f32_16x16x32_bf16 v[112:115], v[174:177], v[182:185], v[112:115]
	v_mfma_f32_16x16x32_bf16 v[100:103], v[166:169], v[190:193], v[100:103]
	v_mfma_f32_16x16x32_bf16 v[96:99], v[174:177], v[190:193], v[96:99]
	v_mfma_f32_16x16x32_bf16 v[84:87], v[166:169], v[198:201], v[84:87]
	v_mfma_f32_16x16x32_bf16 v[80:83], v[174:177], v[198:201], v[80:83]
	v_mfma_f32_16x16x32_bf16 v[68:71], v[166:169], v[206:209], v[68:71]
	v_mfma_f32_16x16x32_bf16 v[64:67], v[174:177], v[206:209], v[64:67]
	v_mfma_f32_16x16x32_bf16 v[124:127], v[154:157], v[186:189], v[124:127]
	v_mfma_f32_16x16x32_bf16 v[120:123], v[162:165], v[186:189], v[120:123]
	v_mfma_f32_16x16x32_bf16 v[108:111], v[154:157], v[194:197], v[108:111]
	v_mfma_f32_16x16x32_bf16 v[104:107], v[162:165], v[194:197], v[104:107]
	v_mfma_f32_16x16x32_bf16 v[92:95], v[154:157], v[202:205], v[92:95]
	v_mfma_f32_16x16x32_bf16 v[88:91], v[162:165], v[202:205], v[88:91]
	v_mfma_f32_16x16x32_bf16 v[76:79], v[154:157], v[210:213], v[76:79]
	v_mfma_f32_16x16x32_bf16 v[72:75], v[162:165], v[210:213], v[72:75]
	v_mfma_f32_16x16x32_bf16 v[116:119], v[170:173], v[186:189], v[116:119]
	v_mfma_f32_16x16x32_bf16 v[112:115], v[178:181], v[186:189], v[112:115]
	v_mfma_f32_16x16x32_bf16 v[100:103], v[170:173], v[194:197], v[100:103]
	v_mfma_f32_16x16x32_bf16 v[96:99], v[178:181], v[194:197], v[96:99]
	v_mfma_f32_16x16x32_bf16 v[84:87], v[170:173], v[202:205], v[84:87]
	v_mfma_f32_16x16x32_bf16 v[80:83], v[178:181], v[202:205], v[80:83]
	v_mfma_f32_16x16x32_bf16 v[68:71], v[170:173], v[210:213], v[68:71]
	v_mfma_f32_16x16x32_bf16 v[64:67], v[178:181], v[210:213], v[64:67]
	s_setprio 0
	s_barrier
	s_add_u32 s52, s52, 0x80
	s_addc_u32 s53, s53, 0
	s_add_i32 s54, s70, s3
	s_mov_b32 m0, s54
	ds_read_b128 v[182:185], v145 offset:49152
	ds_read_b128 v[186:189], v145 offset:50176
	ds_read_b128 v[190:193], v145 offset:51200
	ds_read_b128 v[194:197], v145 offset:52224
	ds_read_b128 v[198:201], v145 offset:53248
	ds_read_b128 v[202:205], v145 offset:54272
	ds_read_b128 v[206:209], v145 offset:55296
	ds_read_b128 v[210:213], v145 offset:56320
	s_nop 0
	global_load_lds_dwordx4 v149, s[52:53]
	s_add_i32 m0, s54, 0x2000
	s_nop 0
	global_load_lds_dwordx4 v128, s[52:53]
	s_add_u32 s52, s56, 0x80
	s_addc_u32 s53, s57, 0
	s_add_i32 s54, s71, s3
	s_mov_b32 m0, s54
	s_nop 0
	global_load_lds_dwordx4 v149, s[52:53]
	s_add_i32 m0, s54, 0x2000
	s_nop 0
	global_load_lds_dwordx4 v128, s[52:53]
	s_waitcnt vmcnt(6)
	s_waitcnt lgkmcnt(0)
	s_barrier
	s_setprio 1
	s_waitcnt lgkmcnt(0)
	v_mfma_f32_16x16x32_bf16 v[60:63], v[150:153], v[182:185], v[60:63]
	v_mfma_f32_16x16x32_bf16 v[56:59], v[158:161], v[182:185], v[56:59]
	v_mfma_f32_16x16x32_bf16 v[44:47], v[150:153], v[190:193], v[44:47]
	v_mfma_f32_16x16x32_bf16 v[40:43], v[158:161], v[190:193], v[40:43]
	v_mfma_f32_16x16x32_bf16 v[28:31], v[150:153], v[198:201], v[28:31]
	v_mfma_f32_16x16x32_bf16 v[24:27], v[158:161], v[198:201], v[24:27]
	v_mfma_f32_16x16x32_bf16 v[12:15], v[150:153], v[206:209], v[12:15]
	v_mfma_f32_16x16x32_bf16 v[8:11], v[158:161], v[206:209], v[8:11]
	v_mfma_f32_16x16x32_bf16 v[52:55], v[166:169], v[182:185], v[52:55]
	v_mfma_f32_16x16x32_bf16 v[48:51], v[174:177], v[182:185], v[48:51]
	v_mfma_f32_16x16x32_bf16 v[36:39], v[166:169], v[190:193], v[36:39]
	v_mfma_f32_16x16x32_bf16 v[32:35], v[174:177], v[190:193], v[32:35]
	v_mfma_f32_16x16x32_bf16 v[20:23], v[166:169], v[198:201], v[20:23]
	v_mfma_f32_16x16x32_bf16 v[16:19], v[174:177], v[198:201], v[16:19]
	v_mfma_f32_16x16x32_bf16 v[4:7], v[166:169], v[206:209], v[4:7]
	v_mfma_f32_16x16x32_bf16 v[0:3], v[174:177], v[206:209], v[0:3]
	v_mfma_f32_16x16x32_bf16 v[60:63], v[154:157], v[186:189], v[60:63]
	v_mfma_f32_16x16x32_bf16 v[56:59], v[162:165], v[186:189], v[56:59]
	v_mfma_f32_16x16x32_bf16 v[44:47], v[154:157], v[194:197], v[44:47]
	v_mfma_f32_16x16x32_bf16 v[40:43], v[162:165], v[194:197], v[40:43]
	v_mfma_f32_16x16x32_bf16 v[28:31], v[154:157], v[202:205], v[28:31]
	v_mfma_f32_16x16x32_bf16 v[24:27], v[162:165], v[202:205], v[24:27]
	v_mfma_f32_16x16x32_bf16 v[12:15], v[154:157], v[210:213], v[12:15]
	v_mfma_f32_16x16x32_bf16 v[8:11], v[162:165], v[210:213], v[8:11]
	v_mfma_f32_16x16x32_bf16 v[52:55], v[170:173], v[186:189], v[52:55]
	v_mfma_f32_16x16x32_bf16 v[48:51], v[178:181], v[186:189], v[48:51]
	v_mfma_f32_16x16x32_bf16 v[36:39], v[170:173], v[194:197], v[36:39]
	v_mfma_f32_16x16x32_bf16 v[32:35], v[178:181], v[194:197], v[32:35]
	v_mfma_f32_16x16x32_bf16 v[20:23], v[170:173], v[202:205], v[20:23]
	v_mfma_f32_16x16x32_bf16 v[16:19], v[178:181], v[202:205], v[16:19]
	v_mfma_f32_16x16x32_bf16 v[4:7], v[170:173], v[210:213], v[4:7]
	v_mfma_f32_16x16x32_bf16 v[0:3], v[178:181], v[210:213], v[0:3]
	s_setprio 0
	s_barrier
	s_add_i32 s69, s69, 2
	s_add_u32 s65, s65, 0x100
	s_addc_u32 s66, s66, 0
	s_add_u32 s67, s67, 0x100
	s_addc_u32 s68, s68, 0
	s_cmp_gt_u32 s69, 29
	s_cbranch_scc0 .LBB0_1207
	s_and_b64 vcc, exec, s[40:41]
	s_cbranch_vccz .LBB0_1210
	s_barrier
; __device__ __forceinline__ unsigned pk2(float lo, float hi) { unsigned r; asm volatile("v_cvt_pk_bf16_f32 %0, %1, %2" : "=v"(r) : "v"(lo), "v"(hi)); return r; }
; __device__ __forceinline__ f32x2 swiglu_pk(f32x2 g, f32x2 u, float rs) {
;     const f32x2 t = g * rs, s = t * (-1.44269504089f);
;     f32x2 e; e.x = __builtin_amdgcn_exp2f(s.x); e.y = __builtin_amdgcn_exp2f(s.y);
;     const f32x2 d = e + 1.0f; f32x2 r; r.x = __builtin_amdgcn_rcpf(d.x); r.y = __builtin_amdgcn_rcpf(d.y);
;     return (t * r) * (u * rs);
; }
;     __device__ __forceinline__ void operator()(const f32x4 (&acc)[2][2][4][2], const Unit& u, int wr, int wc, int fr, int fq) const {
;         const int row0 = u.pm * BM + wr * 64 + fr, col0 = u.pn * 128 + wc * 32 + 8 * fq;
;         float rsv[8];
; #pragma unroll
;         for (int i = 0; i < 8; ++i) rsv[i] = ss[row0 + (i >> 2) * HALF + (i & 3) * 16];
; #pragma unroll
;         for (int i = 0; i < 8; ++i) rsv[i] = __builtin_amdgcn_rsqf(rsv[i] * (1.0f / D) + EPS);
;         __builtin_amdgcn_sched_barrier(0);
; #pragma unroll
;         for (int ai = 0; ai < 2; ++ai)
; #pragma unroll
;             for (int m = 0; m < 4; ++m) {
;                 const int row = row0 + ai * HALF + m * 16;
;                 const float rs = rsv[ai * 4 + m];
;                 const f32x4 g0 = acc[ai][0][m][0], g1 = acc[ai][0][m][1], u0 = acc[ai][1][m][0], u1 = acc[ai][1][m][1];
;                 const f32x2 o0 = swiglu_pk((f32x2){g0[0], g0[1]}, (f32x2){u0[0], u0[1]}, rs), o1 = swiglu_pk((f32x2){g0[2], g0[3]}, (f32x2){u0[2], u0[3]}, rs);
;                 const f32x2 o2 = swiglu_pk((f32x2){g1[0], g1[1]}, (f32x2){u1[0], u1[1]}, rs), o3 = swiglu_pk((f32x2){g1[2], g1[3]}, (f32x2){u1[2], u1[3]}, rs);
;                 u32x4 w; w.x = pk2(o0.x, o0.y); w.y = pk2(o1.x, o1.y); w.z = pk2(o2.x, o2.y); w.w = pk2(o3.x, o3.y);
;                 __builtin_nontemporal_store(w, (u32x4*)(G + (size_t)(row >> 8) * ((size_t)BM * FF) + (size_t)(col0 >> 6) * (BM * BK) + (size_t)(row & 255) * BK + (col0 & 63)));
.LBB0_1210:
	s_lshl_b32 s10, s50, 8
	s_add_i32 s45, s10, s26
	v_or_b32_e32 v154, s45, v129
	v_ashrrev_i32_e32 v155, 31, v154
	v_lshl_add_u64 v[150:151], v[154:155], 2, s[38:39]
	global_load_dword v132, v[150:151], off
	global_load_dword v141, v[150:151], off offset:64
	global_load_dword v142, v[150:151], off offset:128
	global_load_dword v144, v[150:151], off offset:192
	global_load_dword v146, v[150:151], off offset:512
	global_load_dword v148, v[150:151], off offset:576
	global_load_dword v152, v[150:151], off offset:640
	s_nop 0
	global_load_dword v150, v[150:151], off offset:704
	s_lshl_b32 s10, s63, 7
	s_or_b32 s10, s10, s27
	s_waitcnt vmcnt(0)
	v_fmamk_f32 v132, v132, 0x3a000000, v147
	v_fmamk_f32 v141, v141, 0x3a000000, v147
	v_fmamk_f32 v142, v142, 0x3a000000, v147
	v_fmamk_f32 v144, v144, 0x3a000000, v147
	v_fmamk_f32 v146, v146, 0x3a000000, v147
	v_fmamk_f32 v151, v148, 0x3a000000, v147
	v_fmamk_f32 v153, v152, 0x3a000000, v147
	v_fmamk_f32 v155, v150, 0x3a000000, v147
	v_rsq_f32_e32 v132, v132
	v_rsq_f32_e32 v156, v141
	v_rsq_f32_e32 v152, v142
	v_rsq_f32_e32 v150, v144
	v_rsq_f32_e32 v148, v146
	v_rsq_f32_e32 v146, v151
	v_rsq_f32_e32 v144, v153
	v_rsq_f32_e32 v142, v155
	v_add_u32_e32 v151, 0x80, v154
	v_pk_mul_f32 v[124:125], v[124:125], v[132:133] op_sel_hi:[1,0]
	v_pk_mul_f32 v[126:127], v[126:127], v[132:133] op_sel_hi:[1,0]
	v_pk_mul_f32 v[158:159], v[124:125], s[42:43] op_sel_hi:[1,0]
	v_pk_mul_f32 v[160:161], v[126:127], s[42:43] op_sel_hi:[1,0]
	v_exp_f32_e32 v158, v158
	v_exp_f32_e32 v159, v159
	v_exp_f32_e32 v160, v160
	v_exp_f32_e32 v161, v161
	v_pk_mul_f32 v[116:117], v[116:117], v[132:133] op_sel_hi:[1,0]
	v_pk_add_f32 v[158:159], v[158:159], 1.0 op_sel_hi:[1,0]
	v_pk_mul_f32 v[118:119], v[118:119], v[132:133] op_sel_hi:[1,0]
	v_rcp_f32_e32 v158, v158
	v_rcp_f32_e32 v159, v159
	v_pk_add_f32 v[160:161], v[160:161], 1.0 op_sel_hi:[1,0]
	v_pk_mul_f32 v[120:121], v[120:121], v[132:133] op_sel_hi:[1,0]
	v_rcp_f32_e32 v160, v160
	v_rcp_f32_e32 v161, v161
	v_pk_mul_f32 v[124:125], v[124:125], v[158:159]
	v_pk_mul_f32 v[122:123], v[122:123], v[132:133] op_sel_hi:[1,0]
	v_pk_mul_f32 v[116:117], v[116:117], v[124:125]
	v_pk_mul_f32 v[124:125], v[126:127], v[160:161]
	v_pk_mul_f32 v[126:127], v[122:123], s[42:43] op_sel_hi:[1,0]
	v_pk_mul_f32 v[118:119], v[118:119], v[124:125]
	v_pk_mul_f32 v[124:125], v[120:121], s[42:43] op_sel_hi:[1,0]
	v_exp_f32_e32 v126, v126
	v_exp_f32_e32 v124, v124
	v_exp_f32_e32 v125, v125
	v_exp_f32_e32 v127, v127
	s_ashr_i32 s10, s10, 6
	s_ashr_i32 s11, s10, 31
	v_pk_add_f32 v[124:125], v[124:125], 1.0 op_sel_hi:[1,0]
	v_pk_add_f32 v[126:127], v[126:127], 1.0 op_sel_hi:[1,0]
	v_rcp_f32_e32 v124, v124
	v_rcp_f32_e32 v125, v125
	v_rcp_f32_e32 v126, v126
	v_rcp_f32_e32 v127, v127
	s_ashr_i32 s45, s45, 8
	s_lshl_b64 s[10:11], s[10:11], 15
	s_mul_hi_i32 s50, s45, 0x2c0000
	s_mul_i32 s45, s45, 0x2c0000
	v_pk_mul_f32 v[120:121], v[120:121], v[124:125]
	v_pk_mul_f32 v[112:113], v[112:113], v[132:133] op_sel_hi:[1,0]
	s_add_u32 s45, s36, s45
	v_pk_mul_f32 v[120:121], v[112:113], v[120:121]
	v_pk_mul_f32 v[112:113], v[122:123], v[126:127]
	v_pk_mul_f32 v[114:115], v[114:115], v[132:133] op_sel_hi:[1,0]
	s_addc_u32 s50, s37, s50
	v_pk_mul_f32 v[122:123], v[114:115], v[112:113]
	v_cvt_pk_bf16_f32 v112, v116, v117
	s_add_u32 s52, s45, s10
	v_lshlrev_b32_e32 v116, 7, v154
	s_addc_u32 s53, s50, s11
	v_and_b32_e32 v132, 0x6780, v116
	v_lshl_add_u64 v[116:117], s[52:53], 0, v[132:133]
	v_mov_b32_e32 v141, v133
	v_lshl_add_u64 v[116:117], v[116:117], 0, v[140:141]
	v_cvt_pk_bf16_f32 v113, v118, v119
	v_cvt_pk_bf16_f32 v114, v120, v121
	v_cvt_pk_bf16_f32 v115, v122, v123
	global_store_dwordx4 v[116:117], v[112:115], off nt
	v_pk_mul_f32 v[108:109], v[108:109], v[156:157] op_sel_hi:[1,0]
	v_pk_mul_f32 v[110:111], v[110:111], v[156:157] op_sel_hi:[1,0]
	v_pk_mul_f32 v[112:113], v[108:109], s[42:43] op_sel_hi:[1,0]
	v_pk_mul_f32 v[114:115], v[110:111], s[42:43] op_sel_hi:[1,0]
	v_exp_f32_e32 v112, v112
	v_exp_f32_e32 v113, v113
	v_exp_f32_e32 v114, v114
	v_exp_f32_e32 v115, v115
	v_pk_mul_f32 v[100:101], v[100:101], v[156:157] op_sel_hi:[1,0]
	v_pk_add_f32 v[112:113], v[112:113], 1.0 op_sel_hi:[1,0]
	v_pk_mul_f32 v[102:103], v[102:103], v[156:157] op_sel_hi:[1,0]
	v_rcp_f32_e32 v112, v112
	v_rcp_f32_e32 v113, v113
	v_pk_add_f32 v[114:115], v[114:115], 1.0 op_sel_hi:[1,0]
	v_pk_mul_f32 v[104:105], v[104:105], v[156:157] op_sel_hi:[1,0]
	v_rcp_f32_e32 v114, v114
	v_rcp_f32_e32 v115, v115
	v_pk_mul_f32 v[108:109], v[108:109], v[112:113]
	v_pk_mul_f32 v[106:107], v[106:107], v[156:157] op_sel_hi:[1,0]
	v_pk_mul_f32 v[100:101], v[100:101], v[108:109]
	v_pk_mul_f32 v[108:109], v[110:111], v[114:115]
	v_pk_mul_f32 v[110:111], v[106:107], s[42:43] op_sel_hi:[1,0]
	v_pk_mul_f32 v[102:103], v[102:103], v[108:109]
	v_pk_mul_f32 v[108:109], v[104:105], s[42:43] op_sel_hi:[1,0]
	v_exp_f32_e32 v110, v110
	v_exp_f32_e32 v108, v108
	v_exp_f32_e32 v109, v109
	v_exp_f32_e32 v111, v111
	v_pk_mul_f32 v[96:97], v[96:97], v[156:157] op_sel_hi:[1,0]
	v_pk_mul_f32 v[98:99], v[98:99], v[156:157] op_sel_hi:[1,0]
	v_pk_add_f32 v[108:109], v[108:109], 1.0 op_sel_hi:[1,0]
	v_pk_add_f32 v[110:111], v[110:111], 1.0 op_sel_hi:[1,0]
	v_rcp_f32_e32 v108, v108
	v_rcp_f32_e32 v109, v109
	v_rcp_f32_e32 v110, v110
	v_rcp_f32_e32 v111, v111
	v_pk_mul_f32 v[104:105], v[104:105], v[108:109]
	s_nop 0
	v_pk_mul_f32 v[104:105], v[96:97], v[104:105]
	v_pk_mul_f32 v[96:97], v[106:107], v[110:111]
	s_nop 0
	v_pk_mul_f32 v[106:107], v[98:99], v[96:97]
	v_cvt_pk_bf16_f32 v96, v100, v101
	v_cvt_pk_bf16_f32 v97, v102, v103
	v_cvt_pk_bf16_f32 v98, v104, v105
	s_nop 0
; __device__ __forceinline__ unsigned pk2(float lo, float hi) { unsigned r; asm volatile("v_cvt_pk_bf16_f32 %0, %1, %2" : "=v"(r) : "v"(lo), "v"(hi)); return r; }
; __device__ __forceinline__ f32x2 swiglu_pk(f32x2 g, f32x2 u, float rs) {
;     const f32x2 t = g * rs, s = t * (-1.44269504089f);
;     f32x2 e; e.x = __builtin_amdgcn_exp2f(s.x); e.y = __builtin_amdgcn_exp2f(s.y);
;     const f32x2 d = e + 1.0f; f32x2 r; r.x = __builtin_amdgcn_rcpf(d.x); r.y = __builtin_amdgcn_rcpf(d.y);
;     return (t * r) * (u * rs);
; }
;     __device__ __forceinline__ void operator()(const f32x4 (&acc)[2][2][4][2], const Unit& u, int wr, int wc, int fr, int fq) const {
;     ...
; #pragma unroll
;         for (int ai = 0; ai < 2; ++ai)
; #pragma unroll
;             for (int m = 0; m < 4; ++m) {
;                 const int row = row0 + ai * HALF + m * 16;
;                 const float rs = rsv[ai * 4 + m];
;                 const f32x4 g0 = acc[ai][0][m][0], g1 = acc[ai][0][m][1], u0 = acc[ai][1][m][0], u1 = acc[ai][1][m][1];
;                 const f32x2 o0 = swiglu_pk((f32x2){g0[0], g0[1]}, (f32x2){u0[0], u0[1]}, rs), o1 = swiglu_pk((f32x2){g0[2], g0[3]}, (f32x2){u0[2], u0[3]}, rs);
;                 const f32x2 o2 = swiglu_pk((f32x2){g1[0], g1[1]}, (f32x2){u1[0], u1[1]}, rs), o3 = swiglu_pk((f32x2){g1[2], g1[3]}, (f32x2){u1[2], u1[3]}, rs);
;                 u32x4 w; w.x = pk2(o0.x, o0.y); w.y = pk2(o1.x, o1.y); w.z = pk2(o2.x, o2.y); w.w = pk2(o3.x, o3.y);
;                 __builtin_nontemporal_store(w, (u32x4*)(G + (size_t)(row >> 8) * ((size_t)BM * FF) + (size_t)(col0 >> 6) * (BM * BK) + (size_t)(row & 255) * BK + (col0 & 63)));
;                 __builtin_amdgcn_sched_barrier(0);
;             }
	v_cvt_pk_bf16_f32 v99, v106, v107
	global_store_dwordx4 v[116:117], v[96:99], off offset:2048 nt
	v_pk_mul_f32 v[92:93], v[92:93], v[152:153] op_sel_hi:[1,0]
	v_pk_mul_f32 v[94:95], v[94:95], v[152:153] op_sel_hi:[1,0]
	v_pk_mul_f32 v[96:97], v[92:93], s[42:43] op_sel_hi:[1,0]
	v_pk_mul_f32 v[98:99], v[94:95], s[42:43] op_sel_hi:[1,0]
	v_exp_f32_e32 v96, v96
	v_exp_f32_e32 v97, v97
	v_exp_f32_e32 v98, v98
	v_exp_f32_e32 v99, v99
	v_pk_mul_f32 v[84:85], v[84:85], v[152:153] op_sel_hi:[1,0]
	v_pk_add_f32 v[96:97], v[96:97], 1.0 op_sel_hi:[1,0]
	v_pk_mul_f32 v[86:87], v[86:87], v[152:153] op_sel_hi:[1,0]
	v_rcp_f32_e32 v96, v96
	v_rcp_f32_e32 v97, v97
	v_pk_add_f32 v[98:99], v[98:99], 1.0 op_sel_hi:[1,0]
	v_pk_mul_f32 v[88:89], v[88:89], v[152:153] op_sel_hi:[1,0]
	v_rcp_f32_e32 v98, v98
	v_rcp_f32_e32 v99, v99
	v_pk_mul_f32 v[92:93], v[92:93], v[96:97]
	v_pk_mul_f32 v[90:91], v[90:91], v[152:153] op_sel_hi:[1,0]
	v_pk_mul_f32 v[84:85], v[84:85], v[92:93]
	v_pk_mul_f32 v[92:93], v[94:95], v[98:99]
	v_pk_mul_f32 v[94:95], v[90:91], s[42:43] op_sel_hi:[1,0]
	v_pk_mul_f32 v[86:87], v[86:87], v[92:93]
	v_pk_mul_f32 v[92:93], v[88:89], s[42:43] op_sel_hi:[1,0]
	v_exp_f32_e32 v94, v94
	v_exp_f32_e32 v92, v92
	v_exp_f32_e32 v93, v93
	v_exp_f32_e32 v95, v95
	v_pk_mul_f32 v[80:81], v[80:81], v[152:153] op_sel_hi:[1,0]
	v_pk_mul_f32 v[82:83], v[82:83], v[152:153] op_sel_hi:[1,0]
	v_pk_add_f32 v[92:93], v[92:93], 1.0 op_sel_hi:[1,0]
	v_pk_add_f32 v[94:95], v[94:95], 1.0 op_sel_hi:[1,0]
	v_rcp_f32_e32 v92, v92
	v_rcp_f32_e32 v93, v93
	v_rcp_f32_e32 v94, v94
	v_rcp_f32_e32 v95, v95
	v_pk_mul_f32 v[88:89], v[88:89], v[92:93]
	s_nop 0
	v_pk_mul_f32 v[88:89], v[80:81], v[88:89]
	v_pk_mul_f32 v[80:81], v[90:91], v[94:95]
	s_nop 0
	v_pk_mul_f32 v[90:91], v[82:83], v[80:81]
	v_cvt_pk_bf16_f32 v80, v84, v85
	v_add_co_u32_e32 v84, vcc, s61, v116
	v_cvt_pk_bf16_f32 v81, v86, v87
	v_cvt_pk_bf16_f32 v82, v88, v89
	v_cvt_pk_bf16_f32 v83, v90, v91
	s_nop 1
	v_addc_co_u32_e32 v85, vcc, 0, v117, vcc
	global_store_dwordx4 v[84:85], v[80:83], off nt
	v_pk_mul_f32 v[76:77], v[76:77], v[150:151] op_sel_hi:[1,0]
	v_pk_mul_f32 v[78:79], v[78:79], v[150:151] op_sel_hi:[1,0]
	v_pk_mul_f32 v[80:81], v[76:77], s[42:43] op_sel_hi:[1,0]
	v_pk_mul_f32 v[82:83], v[78:79], s[42:43] op_sel_hi:[1,0]
	v_exp_f32_e32 v80, v80
	v_exp_f32_e32 v81, v81
	v_exp_f32_e32 v82, v82
	v_exp_f32_e32 v83, v83
	v_pk_mul_f32 v[68:69], v[68:69], v[150:151] op_sel_hi:[1,0]
	v_pk_add_f32 v[80:81], v[80:81], 1.0 op_sel_hi:[1,0]
	v_pk_mul_f32 v[70:71], v[70:71], v[150:151] op_sel_hi:[1,0]
	v_rcp_f32_e32 v80, v80
	v_rcp_f32_e32 v81, v81
	v_pk_add_f32 v[82:83], v[82:83], 1.0 op_sel_hi:[1,0]
	v_pk_mul_f32 v[72:73], v[72:73], v[150:151] op_sel_hi:[1,0]
	v_rcp_f32_e32 v82, v82
	v_rcp_f32_e32 v83, v83
	v_pk_mul_f32 v[76:77], v[76:77], v[80:81]
	v_pk_mul_f32 v[74:75], v[74:75], v[150:151] op_sel_hi:[1,0]
	v_pk_mul_f32 v[68:69], v[68:69], v[76:77]
	v_pk_mul_f32 v[76:77], v[78:79], v[82:83]
	v_pk_mul_f32 v[78:79], v[74:75], s[42:43] op_sel_hi:[1,0]
	v_pk_mul_f32 v[70:71], v[70:71], v[76:77]
	v_pk_mul_f32 v[76:77], v[72:73], s[42:43] op_sel_hi:[1,0]
	v_exp_f32_e32 v78, v78
	v_exp_f32_e32 v76, v76
	v_exp_f32_e32 v77, v77
	v_exp_f32_e32 v79, v79
	v_pk_mul_f32 v[64:65], v[64:65], v[150:151] op_sel_hi:[1,0]
	v_pk_mul_f32 v[66:67], v[66:67], v[150:151] op_sel_hi:[1,0]
	v_pk_add_f32 v[76:77], v[76:77], 1.0 op_sel_hi:[1,0]
	v_pk_add_f32 v[78:79], v[78:79], 1.0 op_sel_hi:[1,0]
	v_rcp_f32_e32 v76, v76
	v_rcp_f32_e32 v77, v77
	v_rcp_f32_e32 v78, v78
	v_rcp_f32_e32 v79, v79
	v_pk_mul_f32 v[72:73], v[72:73], v[76:77]
	s_nop 0
	v_pk_mul_f32 v[72:73], v[64:65], v[72:73]
	v_pk_mul_f32 v[64:65], v[74:75], v[78:79]
	s_nop 0
	v_pk_mul_f32 v[74:75], v[66:67], v[64:65]
	v_cvt_pk_bf16_f32 v64, v68, v69
	v_cvt_pk_bf16_f32 v65, v70, v71
	v_cvt_pk_bf16_f32 v66, v72, v73
	s_nop 0
	v_cvt_pk_bf16_f32 v67, v74, v75
	global_store_dwordx4 v[84:85], v[64:67], off offset:2048 nt
	v_pk_mul_f32 v[60:61], v[60:61], v[148:149] op_sel_hi:[1,0]
	v_pk_mul_f32 v[62:63], v[62:63], v[148:149] op_sel_hi:[1,0]
	v_pk_mul_f32 v[66:67], v[60:61], s[42:43] op_sel_hi:[1,0]
	v_pk_mul_f32 v[68:69], v[62:63], s[42:43] op_sel_hi:[1,0]
	v_exp_f32_e32 v66, v66
	v_exp_f32_e32 v67, v67
	v_exp_f32_e32 v68, v68
	v_exp_f32_e32 v69, v69
	v_pk_mul_f32 v[52:53], v[52:53], v[148:149] op_sel_hi:[1,0]
	v_pk_add_f32 v[66:67], v[66:67], 1.0 op_sel_hi:[1,0]
	v_pk_mul_f32 v[54:55], v[54:55], v[148:149] op_sel_hi:[1,0]
	v_rcp_f32_e32 v66, v66
	v_rcp_f32_e32 v67, v67
	v_pk_add_f32 v[68:69], v[68:69], 1.0 op_sel_hi:[1,0]
	v_pk_mul_f32 v[56:57], v[56:57], v[148:149] op_sel_hi:[1,0]
	v_rcp_f32_e32 v68, v68
	v_rcp_f32_e32 v69, v69
	v_pk_mul_f32 v[60:61], v[60:61], v[66:67]
	v_pk_mul_f32 v[58:59], v[58:59], v[148:149] op_sel_hi:[1,0]
	v_pk_mul_f32 v[52:53], v[52:53], v[60:61]
	v_pk_mul_f32 v[60:61], v[62:63], v[68:69]
	v_pk_mul_f32 v[62:63], v[58:59], s[42:43] op_sel_hi:[1,0]
	v_pk_mul_f32 v[54:55], v[54:55], v[60:61]
	v_pk_mul_f32 v[60:61], v[56:57], s[42:43] op_sel_hi:[1,0]
	v_exp_f32_e32 v62, v62
	v_exp_f32_e32 v60, v60
	v_exp_f32_e32 v61, v61
	v_exp_f32_e32 v63, v63
	v_lshrrev_b32_e32 v64, 8, v151
	v_pk_mul_f32 v[48:49], v[48:49], v[148:149] op_sel_hi:[1,0]
	v_pk_add_f32 v[60:61], v[60:61], 1.0 op_sel_hi:[1,0]
	v_pk_add_f32 v[62:63], v[62:63], 1.0 op_sel_hi:[1,0]
	v_rcp_f32_e32 v60, v60
	v_rcp_f32_e32 v61, v61
	v_rcp_f32_e32 v62, v62
	v_rcp_f32_e32 v63, v63
	v_mul_hi_i32_i24_e32 v65, 0x2c0000, v64
	v_pk_mul_f32 v[56:57], v[56:57], v[60:61]
	v_mul_i32_i24_e32 v64, 0x2c0000, v64
	v_pk_mul_f32 v[56:57], v[48:49], v[56:57]
	v_pk_mul_f32 v[48:49], v[58:59], v[62:63]
; __device__ __forceinline__ unsigned pk2(float lo, float hi) { unsigned r; asm volatile("v_cvt_pk_bf16_f32 %0, %1, %2" : "=v"(r) : "v"(lo), "v"(hi)); return r; }
; #define PG8_BAR __builtin_amdgcn_s_barrier()
; template <class Epi>
; __device__ __forceinline__ void gemm_phase(LAS unsigned char* lds, const Gemm g, const StaticOrder& S, const Epi& E) {
;     ...
;         if (!has_next) break;
; #pragma unroll
;         for (int a = 0; a < 2; ++a)
; #pragma unroll
;             for (int b = 0; b < 2; ++b)
; #pragma unroll
;                 for (int m = 0; m < 4; ++m)
; #pragma unroll
;                     for (int n = 0; n < 2; ++n) acc[a][b][m][n] = (f32x4){0.f, 0.f, 0.f, 0.f};
;         cur = nxt; cA = nA; cB = nB; ++ui;
;         if (wr == 1) PG8_BAR;
;     __device__ __forceinline__ void operator()(const f32x4 (&acc)[2][2][4][2], const Unit& u, int wr, int wc, int fr, int fq) const {
;     ...
; #pragma unroll
;         for (int ai = 0; ai < 2; ++ai)
; #pragma unroll
;             for (int m = 0; m < 4; ++m) {
;                 const int row = row0 + ai * HALF + m * 16;
;                 const float rs = rsv[ai * 4 + m];
;                 const f32x4 g0 = acc[ai][0][m][0], g1 = acc[ai][0][m][1], u0 = acc[ai][1][m][0], u1 = acc[ai][1][m][1];
;                 const f32x2 o0 = swiglu_pk((f32x2){g0[0], g0[1]}, (f32x2){u0[0], u0[1]}, rs), o1 = swiglu_pk((f32x2){g0[2], g0[3]}, (f32x2){u0[2], u0[3]}, rs);
;                 const f32x2 o2 = swiglu_pk((f32x2){g1[0], g1[1]}, (f32x2){u1[0], u1[1]}, rs), o3 = swiglu_pk((f32x2){g1[2], g1[3]}, (f32x2){u1[2], u1[3]}, rs);
;                 u32x4 w; w.x = pk2(o0.x, o0.y); w.y = pk2(o1.x, o1.y); w.z = pk2(o2.x, o2.y); w.w = pk2(o3.x, o3.y);
;                 __builtin_nontemporal_store(w, (u32x4*)(G + (size_t)(row >> 8) * ((size_t)BM * FF) + (size_t)(col0 >> 6) * (BM * BK) + (size_t)(row & 255) * BK + (col0 & 63)));
;                 __builtin_amdgcn_sched_barrier(0);
;             }
	v_pk_mul_f32 v[50:51], v[50:51], v[148:149] op_sel_hi:[1,0]
	s_nop 0
	v_pk_mul_f32 v[58:59], v[50:51], v[48:49]
	v_cvt_pk_bf16_f32 v48, v52, v53
	v_cvt_pk_bf16_f32 v49, v54, v55
	v_lshl_add_u64 v[52:53], s[36:37], 0, v[64:65]
	v_lshlrev_b32_e32 v54, 7, v151
	v_lshl_add_u64 v[52:53], v[52:53], 0, s[10:11]
	v_and_b32_e32 v132, 0x6780, v54
	v_lshl_add_u64 v[52:53], v[52:53], 0, v[132:133]
	v_lshl_add_u64 v[52:53], v[52:53], 0, v[140:141]
	v_cvt_pk_bf16_f32 v50, v56, v57
	v_cvt_pk_bf16_f32 v51, v58, v59
	global_store_dwordx4 v[52:53], v[48:51], off nt
	v_pk_mul_f32 v[44:45], v[44:45], v[146:147] op_sel_hi:[1,0]
	v_pk_mul_f32 v[46:47], v[46:47], v[146:147] op_sel_hi:[1,0]
	v_pk_mul_f32 v[48:49], v[44:45], s[42:43] op_sel_hi:[1,0]
	v_pk_mul_f32 v[50:51], v[46:47], s[42:43] op_sel_hi:[1,0]
	v_exp_f32_e32 v48, v48
	v_exp_f32_e32 v49, v49
	v_exp_f32_e32 v50, v50
	v_exp_f32_e32 v51, v51
	v_pk_mul_f32 v[36:37], v[36:37], v[146:147] op_sel_hi:[1,0]
	v_pk_add_f32 v[48:49], v[48:49], 1.0 op_sel_hi:[1,0]
	v_pk_mul_f32 v[38:39], v[38:39], v[146:147] op_sel_hi:[1,0]
	v_rcp_f32_e32 v48, v48
	v_rcp_f32_e32 v49, v49
	v_pk_add_f32 v[50:51], v[50:51], 1.0 op_sel_hi:[1,0]
	v_pk_mul_f32 v[40:41], v[40:41], v[146:147] op_sel_hi:[1,0]
	v_rcp_f32_e32 v50, v50
	v_rcp_f32_e32 v51, v51
	v_pk_mul_f32 v[44:45], v[44:45], v[48:49]
	v_pk_mul_f32 v[42:43], v[42:43], v[146:147] op_sel_hi:[1,0]
	v_pk_mul_f32 v[36:37], v[36:37], v[44:45]
	v_pk_mul_f32 v[44:45], v[46:47], v[50:51]
	v_pk_mul_f32 v[46:47], v[42:43], s[42:43] op_sel_hi:[1,0]
	v_pk_mul_f32 v[38:39], v[38:39], v[44:45]
	v_pk_mul_f32 v[44:45], v[40:41], s[42:43] op_sel_hi:[1,0]
	v_exp_f32_e32 v46, v46
	v_exp_f32_e32 v44, v44
	v_exp_f32_e32 v45, v45
	v_exp_f32_e32 v47, v47
	v_pk_mul_f32 v[32:33], v[32:33], v[146:147] op_sel_hi:[1,0]
	v_pk_mul_f32 v[34:35], v[34:35], v[146:147] op_sel_hi:[1,0]
	v_pk_add_f32 v[44:45], v[44:45], 1.0 op_sel_hi:[1,0]
	v_pk_add_f32 v[46:47], v[46:47], 1.0 op_sel_hi:[1,0]
	v_rcp_f32_e32 v44, v44
	v_rcp_f32_e32 v45, v45
	v_rcp_f32_e32 v46, v46
	v_rcp_f32_e32 v47, v47
	v_pk_mul_f32 v[40:41], v[40:41], v[44:45]
	s_nop 0
	v_pk_mul_f32 v[40:41], v[32:33], v[40:41]
	v_pk_mul_f32 v[32:33], v[42:43], v[46:47]
	s_nop 0
	v_pk_mul_f32 v[42:43], v[34:35], v[32:33]
	v_cvt_pk_bf16_f32 v32, v36, v37
	v_cvt_pk_bf16_f32 v33, v38, v39
	v_cvt_pk_bf16_f32 v34, v40, v41
	s_nop 0
	v_cvt_pk_bf16_f32 v35, v42, v43
	global_store_dwordx4 v[52:53], v[32:35], off offset:2048 nt
	v_pk_mul_f32 v[28:29], v[28:29], v[144:145] op_sel_hi:[1,0]
	v_pk_mul_f32 v[30:31], v[30:31], v[144:145] op_sel_hi:[1,0]
	v_pk_mul_f32 v[32:33], v[28:29], s[42:43] op_sel_hi:[1,0]
	v_pk_mul_f32 v[34:35], v[30:31], s[42:43] op_sel_hi:[1,0]
	v_exp_f32_e32 v32, v32
	v_exp_f32_e32 v33, v33
	v_exp_f32_e32 v34, v34
	v_exp_f32_e32 v35, v35
	v_pk_mul_f32 v[20:21], v[20:21], v[144:145] op_sel_hi:[1,0]
	v_pk_add_f32 v[32:33], v[32:33], 1.0 op_sel_hi:[1,0]
	v_pk_mul_f32 v[22:23], v[22:23], v[144:145] op_sel_hi:[1,0]
	v_rcp_f32_e32 v32, v32
	v_rcp_f32_e32 v33, v33
	v_pk_add_f32 v[34:35], v[34:35], 1.0 op_sel_hi:[1,0]
	v_pk_mul_f32 v[24:25], v[24:25], v[144:145] op_sel_hi:[1,0]
	v_rcp_f32_e32 v34, v34
	v_rcp_f32_e32 v35, v35
	v_pk_mul_f32 v[28:29], v[28:29], v[32:33]
	v_pk_mul_f32 v[26:27], v[26:27], v[144:145] op_sel_hi:[1,0]
	v_pk_mul_f32 v[20:21], v[20:21], v[28:29]
	v_pk_mul_f32 v[28:29], v[30:31], v[34:35]
	v_pk_mul_f32 v[30:31], v[26:27], s[42:43] op_sel_hi:[1,0]
	v_pk_mul_f32 v[22:23], v[22:23], v[28:29]
	v_pk_mul_f32 v[28:29], v[24:25], s[42:43] op_sel_hi:[1,0]
	v_exp_f32_e32 v30, v30
	v_exp_f32_e32 v28, v28
	v_exp_f32_e32 v29, v29
	v_exp_f32_e32 v31, v31
	v_pk_mul_f32 v[16:17], v[16:17], v[144:145] op_sel_hi:[1,0]
	v_pk_mul_f32 v[18:19], v[18:19], v[144:145] op_sel_hi:[1,0]
	v_pk_add_f32 v[28:29], v[28:29], 1.0 op_sel_hi:[1,0]
	v_pk_add_f32 v[30:31], v[30:31], 1.0 op_sel_hi:[1,0]
	v_rcp_f32_e32 v28, v28
	v_rcp_f32_e32 v29, v29
	v_rcp_f32_e32 v30, v30
	v_rcp_f32_e32 v31, v31
	v_pk_mul_f32 v[24:25], v[24:25], v[28:29]
	s_nop 0
	v_pk_mul_f32 v[24:25], v[16:17], v[24:25]
	v_pk_mul_f32 v[16:17], v[26:27], v[30:31]
	s_nop 0
	v_pk_mul_f32 v[26:27], v[18:19], v[16:17]
	v_cvt_pk_bf16_f32 v16, v20, v21
	v_add_co_u32_e32 v20, vcc, s61, v52
	v_cvt_pk_bf16_f32 v17, v22, v23
	v_cvt_pk_bf16_f32 v18, v24, v25
	v_cvt_pk_bf16_f32 v19, v26, v27
	s_nop 1
	v_addc_co_u32_e32 v21, vcc, 0, v53, vcc
	global_store_dwordx4 v[20:21], v[16:19], off nt
	v_pk_mul_f32 v[12:13], v[12:13], v[142:143] op_sel_hi:[1,0]
	v_pk_mul_f32 v[14:15], v[14:15], v[142:143] op_sel_hi:[1,0]
	v_pk_mul_f32 v[16:17], v[12:13], s[42:43] op_sel_hi:[1,0]
	v_pk_mul_f32 v[18:19], v[14:15], s[42:43] op_sel_hi:[1,0]
	v_exp_f32_e32 v16, v16
	v_exp_f32_e32 v17, v17
	v_exp_f32_e32 v18, v18
	v_exp_f32_e32 v19, v19
	v_pk_mul_f32 v[4:5], v[4:5], v[142:143] op_sel_hi:[1,0]
	v_pk_add_f32 v[16:17], v[16:17], 1.0 op_sel_hi:[1,0]
	v_pk_mul_f32 v[6:7], v[6:7], v[142:143] op_sel_hi:[1,0]
	v_rcp_f32_e32 v16, v16
	v_rcp_f32_e32 v17, v17
	v_pk_add_f32 v[18:19], v[18:19], 1.0 op_sel_hi:[1,0]
	v_pk_mul_f32 v[8:9], v[8:9], v[142:143] op_sel_hi:[1,0]
	v_rcp_f32_e32 v18, v18
	v_rcp_f32_e32 v19, v19
	v_pk_mul_f32 v[12:13], v[12:13], v[16:17]
	v_pk_mul_f32 v[10:11], v[10:11], v[142:143] op_sel_hi:[1,0]
	v_pk_mul_f32 v[4:5], v[4:5], v[12:13]
	v_pk_mul_f32 v[12:13], v[14:15], v[18:19]
	v_pk_mul_f32 v[14:15], v[10:11], s[42:43] op_sel_hi:[1,0]
	v_pk_mul_f32 v[6:7], v[6:7], v[12:13]
	v_pk_mul_f32 v[12:13], v[8:9], s[42:43] op_sel_hi:[1,0]
	v_exp_f32_e32 v14, v14
	v_exp_f32_e32 v12, v12
	v_exp_f32_e32 v13, v13
	v_exp_f32_e32 v15, v15
	v_pk_mul_f32 v[0:1], v[0:1], v[142:143] op_sel_hi:[1,0]
	v_pk_mul_f32 v[2:3], v[2:3], v[142:143] op_sel_hi:[1,0]
	v_pk_add_f32 v[12:13], v[12:13], 1.0 op_sel_hi:[1,0]
	v_pk_add_f32 v[14:15], v[14:15], 1.0 op_sel_hi:[1,0]
	v_rcp_f32_e32 v12, v12
	v_rcp_f32_e32 v13, v13
	v_rcp_f32_e32 v14, v14
	v_rcp_f32_e32 v15, v15
	v_pk_mul_f32 v[8:9], v[8:9], v[12:13]
	s_nop 0
	v_pk_mul_f32 v[8:9], v[0:1], v[8:9]
	v_pk_mul_f32 v[0:1], v[10:11], v[14:15]
	s_nop 0
	v_pk_mul_f32 v[10:11], v[2:3], v[0:1]
	v_cvt_pk_bf16_f32 v0, v4, v5
	v_cvt_pk_bf16_f32 v1, v6, v7
	v_cvt_pk_bf16_f32 v2, v8, v9
	s_nop 0
	v_cvt_pk_bf16_f32 v3, v10, v11
	global_store_dwordx4 v[20:21], v[0:3], off offset:2048 nt
	s_and_b64 vcc, exec, s[8:9]
	s_mov_b64 s[8:9], -1
	s_cbranch_vccnz .LBB0_1201
	s_andn2_b64 vcc, exec, s[34:35]
	s_cbranch_vccnz .LBB0_1200
	s_barrier
	s_branch .LBB0_1200
